# E5 + E1b: K-loop segment barrier released 4 MFMAs before the end of each MFMA block, trailing MFMAs at s_setprio 2
# speedup vs baseline: 1.0123x; 1.0039x over previous
.LBB0_225:
	ds_read_b128 v[128:131], v157
	ds_read_b128 v[132:135], v157 offset:1024
	ds_read_b128 v[146:149], v157 offset:2048
	ds_read_b128 v[164:167], v157 offset:3072
	ds_read_b128 v[168:171], v159
	ds_read_b128 v[172:175], v159 offset:1024
	ds_read_b128 v[176:179], v159 offset:2048
	ds_read_b128 v[180:183], v159 offset:3072
	s_add_u32 s36, s22, 0xfff80080
	s_addc_u32 s37, s23, -1
	s_cmp_eq_u32 s78, 28
	s_cselect_b32 s81, s5, s37
	s_cselect_b32 s80, s14, s36
	s_cselect_b32 vcc_hi, s20, s45
	s_cselect_b32 vcc_lo, s21, s24
	s_add_i32 m0, s77, 0xc000
	ds_read_b128 v[184:187], v161
	ds_read_b128 v[188:191], v161 offset:1024
	ds_read_b128 v[192:195], v161 offset:2048
	ds_read_b128 v[196:199], v161 offset:3072
	ds_read_b128 v[200:203], v161 offset:4096
	ds_read_b128 v[204:207], v161 offset:5120
	ds_read_b128 v[208:211], v161 offset:6144
	ds_read_b128 v[212:215], v161 offset:7168
	global_load_lds_dwordx4 v140, s[22:23]
	s_add_i32 m0, s77, 0xe000
	s_nop 0
	s_add_u32 s98, s22, s6
	s_addc_u32 s99, s23, s7
	global_load_lds_dwordx4 v140, s[98:99]
	s_waitcnt vmcnt(8)
	s_waitcnt lgkmcnt(0)
	s_barrier
	s_setprio 1
	s_waitcnt lgkmcnt(0)
	v_mfma_i32_16x16x64_i8 v[0:3], v[128:131], v[184:187], v[0:3]
	v_mfma_i32_16x16x64_i8 v[56:59], v[146:149], v[184:187], v[56:59]
	v_mfma_i32_16x16x64_i8 v[4:7], v[128:131], v[192:195], v[4:7]
	v_mfma_i32_16x16x64_i8 v[52:55], v[146:149], v[192:195], v[52:55]
	v_mfma_i32_16x16x64_i8 v[12:15], v[128:131], v[200:203], v[12:15]
	v_mfma_i32_16x16x64_i8 v[48:51], v[146:149], v[200:203], v[48:51]
	v_mfma_i32_16x16x64_i8 v[8:11], v[128:131], v[208:211], v[8:11]
	v_mfma_i32_16x16x64_i8 v[44:47], v[146:149], v[208:211], v[44:47]
	v_mfma_i32_16x16x64_i8 v[0:3], v[132:135], v[188:191], v[0:3]
	v_mfma_i32_16x16x64_i8 v[56:59], v[164:167], v[188:191], v[56:59]
	v_mfma_i32_16x16x64_i8 v[4:7], v[132:135], v[196:199], v[4:7]
	v_mfma_i32_16x16x64_i8 v[52:55], v[164:167], v[196:199], v[52:55]
	v_mfma_i32_16x16x64_i8 v[12:15], v[132:135], v[204:207], v[12:15]
	v_mfma_i32_16x16x64_i8 v[48:51], v[164:167], v[204:207], v[48:51]
	v_mfma_i32_16x16x64_i8 v[8:11], v[132:135], v[212:215], v[8:11]
	v_mfma_i32_16x16x64_i8 v[44:47], v[164:167], v[212:215], v[44:47]
	s_setprio 0
	s_setprio 1
	v_mfma_i32_16x16x64_i8 v[88:91], v[168:171], v[184:187], v[88:91]
	v_mfma_i32_16x16x64_i8 v[120:123], v[176:179], v[184:187], v[120:123]
	v_mfma_i32_16x16x64_i8 v[84:87], v[168:171], v[192:195], v[84:87]
	v_mfma_i32_16x16x64_i8 v[116:119], v[176:179], v[192:195], v[116:119]
	v_mfma_i32_16x16x64_i8 v[80:83], v[168:171], v[200:203], v[80:83]
	v_mfma_i32_16x16x64_i8 v[112:115], v[176:179], v[200:203], v[112:115]
	v_mfma_i32_16x16x64_i8 v[76:79], v[168:171], v[208:211], v[76:79]
	v_mfma_i32_16x16x64_i8 v[108:111], v[176:179], v[208:211], v[108:111]
	v_mfma_i32_16x16x64_i8 v[88:91], v[172:175], v[188:191], v[88:91]
	v_mfma_i32_16x16x64_i8 v[120:123], v[180:183], v[188:191], v[120:123]
	v_mfma_i32_16x16x64_i8 v[84:87], v[172:175], v[196:199], v[84:87]
	v_mfma_i32_16x16x64_i8 v[116:119], v[180:183], v[196:199], v[116:119]
	s_setprio 2
	s_barrier
	v_mfma_i32_16x16x64_i8 v[80:83], v[172:175], v[204:207], v[80:83]
	v_mfma_i32_16x16x64_i8 v[112:115], v[180:183], v[204:207], v[112:115]
	v_mfma_i32_16x16x64_i8 v[76:79], v[172:175], v[212:215], v[76:79]
	v_mfma_i32_16x16x64_i8 v[108:111], v[180:183], v[212:215], v[108:111]
	s_setprio 0
	s_add_i32 s36, s86, s63
	s_mov_b32 m0, s36
	ds_read_b128 v[184:187], v161 offset:16384
	ds_read_b128 v[188:191], v161 offset:17408
	ds_read_b128 v[192:195], v161 offset:18432
	ds_read_b128 v[196:199], v161 offset:19456
	ds_read_b128 v[200:203], v161 offset:20480
	ds_read_b128 v[204:207], v161 offset:21504
	ds_read_b128 v[208:211], v161 offset:22528
	ds_read_b128 v[212:215], v161 offset:23552
	global_load_lds_dwordx4 v138, vcc
	s_add_i32 m0, s36, 0x2000
	s_add_i32 s36, s87, s63
	s_add_u32 s98, vcc_lo, s6
	s_addc_u32 s99, vcc_hi, s7
	global_load_lds_dwordx4 v138, s[98:99]
	s_mov_b32 m0, s36
	s_nop 0
	s_add_u32 s98, vcc_lo, s8
	s_addc_u32 s99, vcc_hi, s9
	global_load_lds_dwordx4 v138, s[98:99]
	s_add_i32 m0, s36, 0x2000
	s_nop 0
	s_add_u32 s98, vcc_lo, s10
	s_addc_u32 s99, vcc_hi, s11
	global_load_lds_dwordx4 v138, s[98:99]
	s_mov_b32 m0, s77
	s_nop 0
	global_load_lds_dwordx4 v136, s[80:81]
	s_mov_b32 m0, s97
	s_nop 0
	s_add_u32 s98, s80, s6
	s_addc_u32 s99, s81, s7
	global_load_lds_dwordx4 v136, s[98:99]
	s_waitcnt vmcnt(8)
	s_waitcnt lgkmcnt(0)
	s_barrier
	s_setprio 1
	s_waitcnt lgkmcnt(0)
	v_mfma_i32_16x16x64_i8 v[20:23], v[128:131], v[184:187], v[20:23]
	v_mfma_i32_16x16x64_i8 v[40:43], v[146:149], v[184:187], v[40:43]
	v_mfma_i32_16x16x64_i8 v[16:19], v[128:131], v[192:195], v[16:19]
	v_mfma_i32_16x16x64_i8 v[36:39], v[146:149], v[192:195], v[36:39]
	v_mfma_i32_16x16x64_i8 v[24:27], v[128:131], v[200:203], v[24:27]
	v_mfma_i32_16x16x64_i8 v[32:35], v[146:149], v[200:203], v[32:35]
	v_mfma_i32_16x16x64_i8 v[28:31], v[128:131], v[208:211], v[28:31]
	v_mfma_i32_16x16x64_i8 v[60:63], v[146:149], v[208:211], v[60:63]
	v_mfma_i32_16x16x64_i8 v[20:23], v[132:135], v[188:191], v[20:23]
	v_mfma_i32_16x16x64_i8 v[40:43], v[164:167], v[188:191], v[40:43]
	v_mfma_i32_16x16x64_i8 v[16:19], v[132:135], v[196:199], v[16:19]
	v_mfma_i32_16x16x64_i8 v[36:39], v[164:167], v[196:199], v[36:39]
	v_mfma_i32_16x16x64_i8 v[24:27], v[132:135], v[204:207], v[24:27]
	v_mfma_i32_16x16x64_i8 v[32:35], v[164:167], v[204:207], v[32:35]
	v_mfma_i32_16x16x64_i8 v[28:31], v[132:135], v[212:215], v[28:31]
	v_mfma_i32_16x16x64_i8 v[60:63], v[164:167], v[212:215], v[60:63]
	s_setprio 0
	s_setprio 1
	v_mfma_i32_16x16x64_i8 v[72:75], v[168:171], v[184:187], v[72:75]
	v_mfma_i32_16x16x64_i8 v[104:107], v[176:179], v[184:187], v[104:107]
	v_mfma_i32_16x16x64_i8 v[68:71], v[168:171], v[192:195], v[68:71]
	v_mfma_i32_16x16x64_i8 v[100:103], v[176:179], v[192:195], v[100:103]
	v_mfma_i32_16x16x64_i8 v[64:67], v[168:171], v[200:203], v[64:67]
	v_mfma_i32_16x16x64_i8 v[96:99], v[176:179], v[200:203], v[96:99]
	v_mfma_i32_16x16x64_i8 v[92:95], v[168:171], v[208:211], v[92:95]
	v_mfma_i32_16x16x64_i8 v[124:127], v[176:179], v[208:211], v[124:127]
	v_mfma_i32_16x16x64_i8 v[72:75], v[172:175], v[188:191], v[72:75]
	v_mfma_i32_16x16x64_i8 v[104:107], v[180:183], v[188:191], v[104:107]
	v_mfma_i32_16x16x64_i8 v[68:71], v[172:175], v[196:199], v[68:71]
	v_mfma_i32_16x16x64_i8 v[100:103], v[180:183], v[196:199], v[100:103]
	s_setprio 2
	s_barrier
	v_mfma_i32_16x16x64_i8 v[64:67], v[172:175], v[204:207], v[64:67]
	v_mfma_i32_16x16x64_i8 v[96:99], v[180:183], v[204:207], v[96:99]
	v_mfma_i32_16x16x64_i8 v[92:95], v[172:175], v[212:215], v[92:95]
	v_mfma_i32_16x16x64_i8 v[124:127], v[180:183], v[212:215], v[124:127]
	s_setprio 0
	s_add_i32 s36, 0, 0x18000
	v_add_u32_e32 v152, s36, v153
	s_add_i32 s37, 0, 0x1c000
	ds_read_b128 v[128:131], v152
	ds_read_b128 v[132:135], v152 offset:1024
	ds_read_b128 v[146:149], v152 offset:2048
	ds_read_b128 v[164:167], v152 offset:3072
	v_add_u32_e32 v152, s37, v153
	ds_read_b128 v[168:171], v152
	ds_read_b128 v[172:175], v152 offset:1024
	ds_read_b128 v[176:179], v152 offset:2048
	ds_read_b128 v[180:183], v152 offset:3072
	s_mov_b32 m0, s33
	ds_read_b128 v[184:187], v161 offset:32768
	ds_read_b128 v[188:191], v161 offset:33792
	ds_read_b128 v[192:195], v161 offset:34816
	ds_read_b128 v[196:199], v161 offset:35840
	ds_read_b128 v[200:203], v161 offset:36864
	ds_read_b128 v[204:207], v161 offset:37888
	ds_read_b128 v[208:211], v161 offset:38912
	ds_read_b128 v[212:215], v161 offset:39936
	s_add_u32 s98, s80, s8
	s_addc_u32 s99, s81, s9
	global_load_lds_dwordx4 v136, s[98:99]
	s_mov_b32 m0, s93
	s_nop 0
	s_add_u32 s98, s80, s10
	s_addc_u32 s99, s81, s11
	global_load_lds_dwordx4 v136, s[98:99]
	s_waitcnt vmcnt(8)
	s_waitcnt lgkmcnt(0)
	s_barrier
	s_setprio 1
	s_waitcnt lgkmcnt(0)
	v_mfma_i32_16x16x64_i8 v[0:3], v[128:131], v[184:187], v[0:3]
	v_mfma_i32_16x16x64_i8 v[56:59], v[146:149], v[184:187], v[56:59]
	v_mfma_i32_16x16x64_i8 v[4:7], v[128:131], v[192:195], v[4:7]
	v_mfma_i32_16x16x64_i8 v[52:55], v[146:149], v[192:195], v[52:55]
	v_mfma_i32_16x16x64_i8 v[12:15], v[128:131], v[200:203], v[12:15]
	v_mfma_i32_16x16x64_i8 v[48:51], v[146:149], v[200:203], v[48:51]
	v_mfma_i32_16x16x64_i8 v[8:11], v[128:131], v[208:211], v[8:11]
	v_mfma_i32_16x16x64_i8 v[44:47], v[146:149], v[208:211], v[44:47]
	v_mfma_i32_16x16x64_i8 v[0:3], v[132:135], v[188:191], v[0:3]
	v_mfma_i32_16x16x64_i8 v[56:59], v[164:167], v[188:191], v[56:59]
	v_mfma_i32_16x16x64_i8 v[4:7], v[132:135], v[196:199], v[4:7]
	v_mfma_i32_16x16x64_i8 v[52:55], v[164:167], v[196:199], v[52:55]
	v_mfma_i32_16x16x64_i8 v[12:15], v[132:135], v[204:207], v[12:15]
	v_mfma_i32_16x16x64_i8 v[48:51], v[164:167], v[204:207], v[48:51]
	v_mfma_i32_16x16x64_i8 v[8:11], v[132:135], v[212:215], v[8:11]
	v_mfma_i32_16x16x64_i8 v[44:47], v[164:167], v[212:215], v[44:47]
	s_setprio 0
	s_setprio 1
	v_mfma_i32_16x16x64_i8 v[88:91], v[168:171], v[184:187], v[88:91]
	v_mfma_i32_16x16x64_i8 v[120:123], v[176:179], v[184:187], v[120:123]
	v_mfma_i32_16x16x64_i8 v[84:87], v[168:171], v[192:195], v[84:87]
	v_mfma_i32_16x16x64_i8 v[116:119], v[176:179], v[192:195], v[116:119]
	v_mfma_i32_16x16x64_i8 v[80:83], v[168:171], v[200:203], v[80:83]
	v_mfma_i32_16x16x64_i8 v[112:115], v[176:179], v[200:203], v[112:115]
	v_mfma_i32_16x16x64_i8 v[76:79], v[168:171], v[208:211], v[76:79]
	v_mfma_i32_16x16x64_i8 v[108:111], v[176:179], v[208:211], v[108:111]
	v_mfma_i32_16x16x64_i8 v[88:91], v[172:175], v[188:191], v[88:91]
	v_mfma_i32_16x16x64_i8 v[120:123], v[180:183], v[188:191], v[120:123]
	v_mfma_i32_16x16x64_i8 v[84:87], v[172:175], v[196:199], v[84:87]
	v_mfma_i32_16x16x64_i8 v[116:119], v[180:183], v[196:199], v[116:119]
	s_setprio 2
	s_barrier
	v_mfma_i32_16x16x64_i8 v[80:83], v[172:175], v[204:207], v[80:83]
	v_mfma_i32_16x16x64_i8 v[112:115], v[180:183], v[204:207], v[112:115]
	v_mfma_i32_16x16x64_i8 v[76:79], v[172:175], v[212:215], v[76:79]
	v_mfma_i32_16x16x64_i8 v[108:111], v[180:183], v[212:215], v[108:111]
	s_setprio 0
	s_add_i32 s36, s36, s63
	s_mov_b32 m0, s36
	ds_read_b128 v[184:187], v161 offset:49152
	ds_read_b128 v[188:191], v161 offset:50176
	ds_read_b128 v[192:195], v161 offset:51200
	ds_read_b128 v[196:199], v161 offset:52224
	ds_read_b128 v[200:203], v161 offset:53248
	ds_read_b128 v[204:207], v161 offset:54272
	ds_read_b128 v[208:211], v161 offset:55296
	ds_read_b128 v[212:215], v161 offset:56320
	s_add_u32 s98, vcc_lo, s46
	s_addc_u32 s99, vcc_hi, s47
	global_load_lds_dwordx4 v138, s[98:99]
	s_add_i32 m0, s36, 0x2000
	s_add_i32 s36, s37, s63
	s_add_u32 s98, vcc_lo, s48
	s_addc_u32 s99, vcc_hi, s49
	global_load_lds_dwordx4 v138, s[98:99]
	s_mov_b32 m0, s36
	s_add_u32 s98, vcc_lo, s54
	s_addc_u32 s99, vcc_hi, s55
	global_load_lds_dwordx4 v138, s[98:99]
	s_add_i32 m0, s36, 0x2000
	s_nop 0
	s_add_u32 s98, vcc_lo, s56
	s_addc_u32 s99, vcc_hi, s57
	global_load_lds_dwordx4 v138, s[98:99]
	s_mov_b32 m0, s95
	s_nop 0
	s_add_u32 s98, s80, s46
	s_addc_u32 s99, s81, s47
	global_load_lds_dwordx4 v136, s[98:99]
	s_mov_b32 m0, s82
	s_nop 0
	s_add_u32 s98, s80, s48
	s_addc_u32 s99, s81, s49
	global_load_lds_dwordx4 v136, s[98:99]
	s_waitcnt vmcnt(8)
	s_waitcnt lgkmcnt(0)
	s_barrier
	s_setprio 1
	s_waitcnt lgkmcnt(0)
	v_mfma_i32_16x16x64_i8 v[20:23], v[128:131], v[184:187], v[20:23]
	v_mfma_i32_16x16x64_i8 v[40:43], v[146:149], v[184:187], v[40:43]
	v_mfma_i32_16x16x64_i8 v[16:19], v[128:131], v[192:195], v[16:19]
	v_mfma_i32_16x16x64_i8 v[36:39], v[146:149], v[192:195], v[36:39]
	v_mfma_i32_16x16x64_i8 v[24:27], v[128:131], v[200:203], v[24:27]
	v_mfma_i32_16x16x64_i8 v[32:35], v[146:149], v[200:203], v[32:35]
	v_mfma_i32_16x16x64_i8 v[28:31], v[128:131], v[208:211], v[28:31]
	v_mfma_i32_16x16x64_i8 v[60:63], v[146:149], v[208:211], v[60:63]
	v_mfma_i32_16x16x64_i8 v[20:23], v[132:135], v[188:191], v[20:23]
	v_mfma_i32_16x16x64_i8 v[40:43], v[164:167], v[188:191], v[40:43]
	v_mfma_i32_16x16x64_i8 v[16:19], v[132:135], v[196:199], v[16:19]
	v_mfma_i32_16x16x64_i8 v[36:39], v[164:167], v[196:199], v[36:39]
	v_mfma_i32_16x16x64_i8 v[24:27], v[132:135], v[204:207], v[24:27]
	v_mfma_i32_16x16x64_i8 v[32:35], v[164:167], v[204:207], v[32:35]
	v_mfma_i32_16x16x64_i8 v[28:31], v[132:135], v[212:215], v[28:31]
	v_mfma_i32_16x16x64_i8 v[60:63], v[164:167], v[212:215], v[60:63]
	s_setprio 0
	s_setprio 1
	v_mfma_i32_16x16x64_i8 v[72:75], v[168:171], v[184:187], v[72:75]
	v_mfma_i32_16x16x64_i8 v[104:107], v[176:179], v[184:187], v[104:107]
	v_mfma_i32_16x16x64_i8 v[68:71], v[168:171], v[192:195], v[68:71]
	v_mfma_i32_16x16x64_i8 v[100:103], v[176:179], v[192:195], v[100:103]
	v_mfma_i32_16x16x64_i8 v[64:67], v[168:171], v[200:203], v[64:67]
	v_mfma_i32_16x16x64_i8 v[96:99], v[176:179], v[200:203], v[96:99]
	v_mfma_i32_16x16x64_i8 v[92:95], v[168:171], v[208:211], v[92:95]
	v_mfma_i32_16x16x64_i8 v[124:127], v[176:179], v[208:211], v[124:127]
	v_mfma_i32_16x16x64_i8 v[72:75], v[172:175], v[188:191], v[72:75]
	v_mfma_i32_16x16x64_i8 v[104:107], v[180:183], v[188:191], v[104:107]
	v_mfma_i32_16x16x64_i8 v[68:71], v[172:175], v[196:199], v[68:71]
	v_mfma_i32_16x16x64_i8 v[100:103], v[180:183], v[196:199], v[100:103]
	s_setprio 2
	s_barrier
	v_mfma_i32_16x16x64_i8 v[64:67], v[172:175], v[204:207], v[64:67]
	v_mfma_i32_16x16x64_i8 v[96:99], v[180:183], v[204:207], v[96:99]
	v_mfma_i32_16x16x64_i8 v[92:95], v[172:175], v[212:215], v[92:95]
	v_mfma_i32_16x16x64_i8 v[124:127], v[180:183], v[212:215], v[124:127]
	s_setprio 0
	s_add_i32 s78, s78, 2
	s_add_u32 s24, s24, 0x100
	s_addc_u32 s45, s45, 0
	s_add_u32 s22, s22, 0x100
	s_addc_u32 s23, s23, 0
	s_cmp_gt_u32 s78, 29
	s_cbranch_scc0 .LBB0_225
	v_readlane_b32 s14, v250, 9
	v_readlane_b32 s15, v250, 10
	s_and_b64 vcc, exec, s[14:15]
	s_cbranch_vccz .LBB0_228
	s_barrier

.LBB0_298:
	ds_read_b128 v[128:131], v153
	ds_read_b128 v[132:135], v153 offset:1024
	ds_read_b128 v[146:149], v153 offset:2048
	ds_read_b128 v[158:161], v153 offset:3072
	ds_read_b128 v[162:165], v154
	ds_read_b128 v[166:169], v154 offset:1024
	ds_read_b128 v[170:173], v154 offset:2048
	ds_read_b128 v[174:177], v154 offset:3072
	s_add_u32 s36, s78, 0xfff00080
	s_addc_u32 s37, s79, -1
	s_cmp_eq_u32 s81, 60
	s_cselect_b32 s97, s5, s37
	s_cselect_b32 s96, s14, s36
	s_cselect_b32 vcc_hi, s20, s80
	s_cselect_b32 vcc_lo, s21, s22
	s_add_i32 m0, s33, 0xc000
	ds_read_b128 v[178:181], v155
	ds_read_b128 v[182:185], v155 offset:1024
	ds_read_b128 v[186:189], v155 offset:2048
	ds_read_b128 v[190:193], v155 offset:3072
	ds_read_b128 v[194:197], v155 offset:4096
	ds_read_b128 v[198:201], v155 offset:5120
	ds_read_b128 v[202:205], v155 offset:6144
	ds_read_b128 v[206:209], v155 offset:7168
	global_load_lds_dwordx4 v140, s[78:79]
	s_add_i32 m0, s33, 0xe000
	s_nop 0
	s_add_u32 s98, s78, s0
	s_addc_u32 s99, s79, s1
	global_load_lds_dwordx4 v140, s[98:99]
	s_waitcnt vmcnt(8)
	s_waitcnt lgkmcnt(0)
	s_barrier
	s_setprio 1
	s_waitcnt lgkmcnt(0)
	v_mfma_f32_16x16x32_bf16 v[124:127], v[128:131], v[178:181], v[124:127]
	v_mfma_f32_16x16x32_bf16 v[120:123], v[146:149], v[178:181], v[120:123]
	v_mfma_f32_16x16x32_bf16 v[112:115], v[128:131], v[186:189], v[112:115]
	v_mfma_f32_16x16x32_bf16 v[108:111], v[146:149], v[186:189], v[108:111]
	v_mfma_f32_16x16x32_bf16 v[100:103], v[128:131], v[194:197], v[100:103]
	v_mfma_f32_16x16x32_bf16 v[92:95], v[146:149], v[194:197], v[92:95]
	v_mfma_f32_16x16x32_bf16 v[84:87], v[128:131], v[202:205], v[84:87]
	v_mfma_f32_16x16x32_bf16 v[76:79], v[146:149], v[202:205], v[76:79]
	v_mfma_f32_16x16x32_bf16 v[124:127], v[132:135], v[182:185], v[124:127]
	v_mfma_f32_16x16x32_bf16 v[120:123], v[158:161], v[182:185], v[120:123]
	v_mfma_f32_16x16x32_bf16 v[112:115], v[132:135], v[190:193], v[112:115]
	v_mfma_f32_16x16x32_bf16 v[108:111], v[158:161], v[190:193], v[108:111]
	v_mfma_f32_16x16x32_bf16 v[100:103], v[132:135], v[198:201], v[100:103]
	v_mfma_f32_16x16x32_bf16 v[92:95], v[158:161], v[198:201], v[92:95]
	v_mfma_f32_16x16x32_bf16 v[84:87], v[132:135], v[206:209], v[84:87]
	v_mfma_f32_16x16x32_bf16 v[76:79], v[158:161], v[206:209], v[76:79]
	s_setprio 0
	s_setprio 1
	v_mfma_f32_16x16x32_bf16 v[116:119], v[162:165], v[178:181], v[116:119]
	v_mfma_f32_16x16x32_bf16 v[104:107], v[170:173], v[178:181], v[104:107]
	v_mfma_f32_16x16x32_bf16 v[96:99], v[162:165], v[186:189], v[96:99]
	v_mfma_f32_16x16x32_bf16 v[88:91], v[170:173], v[186:189], v[88:91]
	v_mfma_f32_16x16x32_bf16 v[80:83], v[162:165], v[194:197], v[80:83]
	v_mfma_f32_16x16x32_bf16 v[72:75], v[170:173], v[194:197], v[72:75]
	v_mfma_f32_16x16x32_bf16 v[68:71], v[162:165], v[202:205], v[68:71]
	v_mfma_f32_16x16x32_bf16 v[64:67], v[170:173], v[202:205], v[64:67]
	v_mfma_f32_16x16x32_bf16 v[116:119], v[166:169], v[182:185], v[116:119]
	v_mfma_f32_16x16x32_bf16 v[104:107], v[174:177], v[182:185], v[104:107]
	v_mfma_f32_16x16x32_bf16 v[96:99], v[166:169], v[190:193], v[96:99]
	v_mfma_f32_16x16x32_bf16 v[88:91], v[174:177], v[190:193], v[88:91]
	s_setprio 2
	s_barrier
	v_mfma_f32_16x16x32_bf16 v[80:83], v[166:169], v[198:201], v[80:83]
	v_mfma_f32_16x16x32_bf16 v[72:75], v[174:177], v[198:201], v[72:75]
	v_mfma_f32_16x16x32_bf16 v[68:71], v[166:169], v[206:209], v[68:71]
	v_mfma_f32_16x16x32_bf16 v[64:67], v[174:177], v[206:209], v[64:67]
	s_setprio 0
	s_add_i32 s36, s82, s63
	s_mov_b32 m0, s36
	ds_read_b128 v[178:181], v155 offset:16384
	ds_read_b128 v[182:185], v155 offset:17408
	ds_read_b128 v[186:189], v155 offset:18432
	ds_read_b128 v[190:193], v155 offset:19456
	ds_read_b128 v[194:197], v155 offset:20480
	ds_read_b128 v[198:201], v155 offset:21504
	ds_read_b128 v[202:205], v155 offset:22528
	ds_read_b128 v[206:209], v155 offset:23552
	global_load_lds_dwordx4 v138, vcc
	s_add_i32 m0, s36, 0x2000
	s_add_i32 s36, s83, s63
	s_add_u32 s98, vcc_lo, s0
	s_addc_u32 s99, vcc_hi, s1
	global_load_lds_dwordx4 v138, s[98:99]
	s_mov_b32 m0, s36
	s_nop 0
	s_add_u32 s98, vcc_lo, s6
	s_addc_u32 s99, vcc_hi, s7
	global_load_lds_dwordx4 v138, s[98:99]
	s_add_i32 m0, s36, 0x2000
	s_nop 0
	s_add_u32 s98, vcc_lo, s8
	s_addc_u32 s99, vcc_hi, s9
	global_load_lds_dwordx4 v138, s[98:99]
	s_mov_b32 m0, s33
	s_nop 0
	global_load_lds_dwordx4 v136, s[96:97]
	s_mov_b32 m0, s55
	s_nop 0
	s_add_u32 s98, s96, s0
	s_addc_u32 s99, s97, s1
	global_load_lds_dwordx4 v136, s[98:99]
	s_waitcnt vmcnt(8)
	s_waitcnt lgkmcnt(0)
	s_barrier
	s_setprio 1
	s_waitcnt lgkmcnt(0)
	v_mfma_f32_16x16x32_bf16 v[60:63], v[128:131], v[178:181], v[60:63]
	v_mfma_f32_16x16x32_bf16 v[56:59], v[146:149], v[178:181], v[56:59]
	v_mfma_f32_16x16x32_bf16 v[52:55], v[128:131], v[186:189], v[52:55]
	v_mfma_f32_16x16x32_bf16 v[44:47], v[146:149], v[186:189], v[44:47]
	v_mfma_f32_16x16x32_bf16 v[36:39], v[128:131], v[194:197], v[36:39]
	v_mfma_f32_16x16x32_bf16 v[28:31], v[146:149], v[194:197], v[28:31]
	v_mfma_f32_16x16x32_bf16 v[20:23], v[128:131], v[202:205], v[20:23]
	v_mfma_f32_16x16x32_bf16 v[12:15], v[146:149], v[202:205], v[12:15]
	v_mfma_f32_16x16x32_bf16 v[60:63], v[132:135], v[182:185], v[60:63]
	v_mfma_f32_16x16x32_bf16 v[56:59], v[158:161], v[182:185], v[56:59]
	v_mfma_f32_16x16x32_bf16 v[52:55], v[132:135], v[190:193], v[52:55]
	v_mfma_f32_16x16x32_bf16 v[44:47], v[158:161], v[190:193], v[44:47]
	v_mfma_f32_16x16x32_bf16 v[36:39], v[132:135], v[198:201], v[36:39]
	v_mfma_f32_16x16x32_bf16 v[28:31], v[158:161], v[198:201], v[28:31]
	v_mfma_f32_16x16x32_bf16 v[20:23], v[132:135], v[206:209], v[20:23]
	v_mfma_f32_16x16x32_bf16 v[12:15], v[158:161], v[206:209], v[12:15]
	s_setprio 0
	s_setprio 1
	v_mfma_f32_16x16x32_bf16 v[48:51], v[162:165], v[178:181], v[48:51]
	v_mfma_f32_16x16x32_bf16 v[40:43], v[170:173], v[178:181], v[40:43]
	v_mfma_f32_16x16x32_bf16 v[32:35], v[162:165], v[186:189], v[32:35]
	v_mfma_f32_16x16x32_bf16 v[24:27], v[170:173], v[186:189], v[24:27]
	v_mfma_f32_16x16x32_bf16 v[16:19], v[162:165], v[194:197], v[16:19]
	v_mfma_f32_16x16x32_bf16 v[8:11], v[170:173], v[194:197], v[8:11]
	v_mfma_f32_16x16x32_bf16 v[4:7], v[162:165], v[202:205], v[4:7]
	v_mfma_f32_16x16x32_bf16 v[0:3], v[170:173], v[202:205], v[0:3]
	v_mfma_f32_16x16x32_bf16 v[48:51], v[166:169], v[182:185], v[48:51]
	v_mfma_f32_16x16x32_bf16 v[40:43], v[174:177], v[182:185], v[40:43]
	v_mfma_f32_16x16x32_bf16 v[32:35], v[166:169], v[190:193], v[32:35]
	v_mfma_f32_16x16x32_bf16 v[24:27], v[174:177], v[190:193], v[24:27]
	s_setprio 2
	s_barrier
	v_mfma_f32_16x16x32_bf16 v[16:19], v[166:169], v[198:201], v[16:19]
	v_mfma_f32_16x16x32_bf16 v[8:11], v[174:177], v[198:201], v[8:11]
	v_mfma_f32_16x16x32_bf16 v[4:7], v[166:169], v[206:209], v[4:7]
	v_mfma_f32_16x16x32_bf16 v[0:3], v[174:177], v[206:209], v[0:3]
	s_setprio 0
	s_add_i32 s36, 0, 0x18000
	v_add_u32_e32 v157, s36, v152
	s_add_i32 s37, 0, 0x1c000
	ds_read_b128 v[128:131], v157
	ds_read_b128 v[132:135], v157 offset:1024
	ds_read_b128 v[146:149], v157 offset:2048
	ds_read_b128 v[158:161], v157 offset:3072
	v_add_u32_e32 v157, s37, v152
	ds_read_b128 v[162:165], v157
	ds_read_b128 v[166:169], v157 offset:1024
	ds_read_b128 v[170:173], v157 offset:2048
	ds_read_b128 v[174:177], v157 offset:3072
	s_mov_b32 m0, s57
	ds_read_b128 v[178:181], v155 offset:32768
	ds_read_b128 v[182:185], v155 offset:33792
	ds_read_b128 v[186:189], v155 offset:34816
	ds_read_b128 v[190:193], v155 offset:35840
	ds_read_b128 v[194:197], v155 offset:36864
	ds_read_b128 v[198:201], v155 offset:37888
	ds_read_b128 v[202:205], v155 offset:38912
	ds_read_b128 v[206:209], v155 offset:39936
	s_add_u32 s98, s96, s6
	s_addc_u32 s99, s97, s7
	global_load_lds_dwordx4 v136, s[98:99]
	s_mov_b32 m0, s59
	s_nop 0
	s_add_u32 s98, s96, s8
	s_addc_u32 s99, s97, s9
	global_load_lds_dwordx4 v136, s[98:99]
	s_waitcnt vmcnt(8)
	s_waitcnt lgkmcnt(0)
	s_barrier
	s_setprio 1
	s_waitcnt lgkmcnt(0)
	v_mfma_f32_16x16x32_bf16 v[124:127], v[128:131], v[178:181], v[124:127]
	v_mfma_f32_16x16x32_bf16 v[120:123], v[146:149], v[178:181], v[120:123]
	v_mfma_f32_16x16x32_bf16 v[112:115], v[128:131], v[186:189], v[112:115]
	v_mfma_f32_16x16x32_bf16 v[108:111], v[146:149], v[186:189], v[108:111]
	v_mfma_f32_16x16x32_bf16 v[100:103], v[128:131], v[194:197], v[100:103]
	v_mfma_f32_16x16x32_bf16 v[92:95], v[146:149], v[194:197], v[92:95]
	v_mfma_f32_16x16x32_bf16 v[84:87], v[128:131], v[202:205], v[84:87]
	v_mfma_f32_16x16x32_bf16 v[76:79], v[146:149], v[202:205], v[76:79]
	v_mfma_f32_16x16x32_bf16 v[124:127], v[132:135], v[182:185], v[124:127]
	v_mfma_f32_16x16x32_bf16 v[120:123], v[158:161], v[182:185], v[120:123]
	v_mfma_f32_16x16x32_bf16 v[112:115], v[132:135], v[190:193], v[112:115]
	v_mfma_f32_16x16x32_bf16 v[108:111], v[158:161], v[190:193], v[108:111]
	v_mfma_f32_16x16x32_bf16 v[100:103], v[132:135], v[198:201], v[100:103]
	v_mfma_f32_16x16x32_bf16 v[92:95], v[158:161], v[198:201], v[92:95]
	v_mfma_f32_16x16x32_bf16 v[84:87], v[132:135], v[206:209], v[84:87]
	v_mfma_f32_16x16x32_bf16 v[76:79], v[158:161], v[206:209], v[76:79]
	s_setprio 0
	s_setprio 1
	v_mfma_f32_16x16x32_bf16 v[116:119], v[162:165], v[178:181], v[116:119]
	v_mfma_f32_16x16x32_bf16 v[104:107], v[170:173], v[178:181], v[104:107]
	v_mfma_f32_16x16x32_bf16 v[96:99], v[162:165], v[186:189], v[96:99]
	v_mfma_f32_16x16x32_bf16 v[88:91], v[170:173], v[186:189], v[88:91]
	v_mfma_f32_16x16x32_bf16 v[80:83], v[162:165], v[194:197], v[80:83]
	v_mfma_f32_16x16x32_bf16 v[72:75], v[170:173], v[194:197], v[72:75]
	v_mfma_f32_16x16x32_bf16 v[68:71], v[162:165], v[202:205], v[68:71]
	v_mfma_f32_16x16x32_bf16 v[64:67], v[170:173], v[202:205], v[64:67]
	v_mfma_f32_16x16x32_bf16 v[116:119], v[166:169], v[182:185], v[116:119]
	v_mfma_f32_16x16x32_bf16 v[104:107], v[174:177], v[182:185], v[104:107]
	v_mfma_f32_16x16x32_bf16 v[96:99], v[166:169], v[190:193], v[96:99]
	v_mfma_f32_16x16x32_bf16 v[88:91], v[174:177], v[190:193], v[88:91]
	s_setprio 2
	s_barrier
	v_mfma_f32_16x16x32_bf16 v[80:83], v[166:169], v[198:201], v[80:83]
	v_mfma_f32_16x16x32_bf16 v[72:75], v[174:177], v[198:201], v[72:75]
	v_mfma_f32_16x16x32_bf16 v[68:71], v[166:169], v[206:209], v[68:71]
	v_mfma_f32_16x16x32_bf16 v[64:67], v[174:177], v[206:209], v[64:67]
	s_setprio 0
	s_add_i32 s36, s36, s63
	s_mov_b32 m0, s36
	ds_read_b128 v[178:181], v155 offset:49152
	ds_read_b128 v[182:185], v155 offset:50176
	ds_read_b128 v[186:189], v155 offset:51200
	ds_read_b128 v[190:193], v155 offset:52224
	ds_read_b128 v[194:197], v155 offset:53248
	ds_read_b128 v[198:201], v155 offset:54272
	ds_read_b128 v[202:205], v155 offset:55296
	ds_read_b128 v[206:209], v155 offset:56320
	s_add_u32 s98, vcc_lo, s24
	s_addc_u32 s99, vcc_hi, s25
	global_load_lds_dwordx4 v138, s[98:99]
	s_add_i32 m0, s36, 0x2000
	s_add_i32 s36, s37, s63
	s_add_u32 s98, vcc_lo, s34
	s_addc_u32 s99, vcc_hi, s35
	global_load_lds_dwordx4 v138, s[98:99]
	s_mov_b32 m0, s36
	s_add_u32 s98, vcc_lo, s12
	s_addc_u32 s99, vcc_hi, s13
	global_load_lds_dwordx4 v138, s[98:99]
	s_add_i32 m0, s36, 0x2000
	s_nop 0
	s_add_u32 s98, vcc_lo, s18
	s_addc_u32 s99, vcc_hi, s19
	global_load_lds_dwordx4 v138, s[98:99]
	s_mov_b32 m0, s68
	s_nop 0
	s_add_u32 s98, s96, s24
	s_addc_u32 s99, s97, s25
	global_load_lds_dwordx4 v136, s[98:99]
	s_mov_b32 m0, s69
	s_nop 0
	s_add_u32 s98, s96, s34
	s_addc_u32 s99, s97, s35
	global_load_lds_dwordx4 v136, s[98:99]
	s_waitcnt vmcnt(8)
	s_waitcnt lgkmcnt(0)
	s_barrier
	s_setprio 1
	s_waitcnt lgkmcnt(0)
	v_mfma_f32_16x16x32_bf16 v[60:63], v[128:131], v[178:181], v[60:63]
	v_mfma_f32_16x16x32_bf16 v[56:59], v[146:149], v[178:181], v[56:59]
	v_mfma_f32_16x16x32_bf16 v[52:55], v[128:131], v[186:189], v[52:55]
	v_mfma_f32_16x16x32_bf16 v[44:47], v[146:149], v[186:189], v[44:47]
	v_mfma_f32_16x16x32_bf16 v[36:39], v[128:131], v[194:197], v[36:39]
	v_mfma_f32_16x16x32_bf16 v[28:31], v[146:149], v[194:197], v[28:31]
	v_mfma_f32_16x16x32_bf16 v[20:23], v[128:131], v[202:205], v[20:23]
	v_mfma_f32_16x16x32_bf16 v[12:15], v[146:149], v[202:205], v[12:15]
	v_mfma_f32_16x16x32_bf16 v[60:63], v[132:135], v[182:185], v[60:63]
	v_mfma_f32_16x16x32_bf16 v[56:59], v[158:161], v[182:185], v[56:59]
	v_mfma_f32_16x16x32_bf16 v[52:55], v[132:135], v[190:193], v[52:55]
	v_mfma_f32_16x16x32_bf16 v[44:47], v[158:161], v[190:193], v[44:47]
	v_mfma_f32_16x16x32_bf16 v[36:39], v[132:135], v[198:201], v[36:39]
	v_mfma_f32_16x16x32_bf16 v[28:31], v[158:161], v[198:201], v[28:31]
	v_mfma_f32_16x16x32_bf16 v[20:23], v[132:135], v[206:209], v[20:23]
	v_mfma_f32_16x16x32_bf16 v[12:15], v[158:161], v[206:209], v[12:15]
	s_setprio 0
	s_setprio 1
	v_mfma_f32_16x16x32_bf16 v[48:51], v[162:165], v[178:181], v[48:51]
	v_mfma_f32_16x16x32_bf16 v[40:43], v[170:173], v[178:181], v[40:43]
	v_mfma_f32_16x16x32_bf16 v[32:35], v[162:165], v[186:189], v[32:35]
	v_mfma_f32_16x16x32_bf16 v[24:27], v[170:173], v[186:189], v[24:27]
	v_mfma_f32_16x16x32_bf16 v[16:19], v[162:165], v[194:197], v[16:19]
	v_mfma_f32_16x16x32_bf16 v[8:11], v[170:173], v[194:197], v[8:11]
	v_mfma_f32_16x16x32_bf16 v[4:7], v[162:165], v[202:205], v[4:7]
	v_mfma_f32_16x16x32_bf16 v[0:3], v[170:173], v[202:205], v[0:3]
	v_mfma_f32_16x16x32_bf16 v[48:51], v[166:169], v[182:185], v[48:51]
	v_mfma_f32_16x16x32_bf16 v[40:43], v[174:177], v[182:185], v[40:43]
	v_mfma_f32_16x16x32_bf16 v[32:35], v[166:169], v[190:193], v[32:35]
	v_mfma_f32_16x16x32_bf16 v[24:27], v[174:177], v[190:193], v[24:27]
	s_setprio 2
	s_barrier
	v_mfma_f32_16x16x32_bf16 v[16:19], v[166:169], v[198:201], v[16:19]
	v_mfma_f32_16x16x32_bf16 v[8:11], v[174:177], v[198:201], v[8:11]
	v_mfma_f32_16x16x32_bf16 v[4:7], v[166:169], v[206:209], v[4:7]
	v_mfma_f32_16x16x32_bf16 v[0:3], v[174:177], v[206:209], v[0:3]
	s_setprio 0
	s_add_i32 s81, s81, 2
	s_add_u32 s22, s22, 0x100
	s_addc_u32 s80, s80, 0
	s_add_u32 s78, s78, 0x100
	s_addc_u32 s79, s79, 0
	s_cmp_gt_u32 s81, 61
	s_cbranch_scc0 .LBB0_298
	s_and_b64 vcc, exec, s[26:27]
	s_cbranch_vccz .LBB0_301
	s_barrier

.LBB0_627:
	ds_read_b128 v[128:131], v151
	ds_read_b128 v[142:145], v151 offset:1024
	ds_read_b128 v[146:149], v151 offset:2048
	ds_read_b128 v[154:157], v151 offset:3072
	ds_read_b128 v[158:161], v152
	ds_read_b128 v[162:165], v152 offset:1024
	ds_read_b128 v[166:169], v152 offset:2048
	ds_read_b128 v[170:173], v152 offset:3072
	s_add_u32 s50, s60, 0xfff00080
	s_addc_u32 s51, s61, -1
	s_cmp_eq_u32 s62, 60
	s_cselect_b32 s77, s5, s51
	s_cselect_b32 s76, s49, s50
	s_cselect_b32 s79, s47, s75
	s_cselect_b32 s78, s59, s74
	s_add_i32 m0, s20, 0xc000
	ds_read_b128 v[174:177], v153
	ds_read_b128 v[178:181], v153 offset:1024
	ds_read_b128 v[182:185], v153 offset:2048
	ds_read_b128 v[186:189], v153 offset:3072
	ds_read_b128 v[190:193], v153 offset:4096
	ds_read_b128 v[194:197], v153 offset:5120
	ds_read_b128 v[198:201], v153 offset:6144
	ds_read_b128 v[202:205], v153 offset:7168
	global_load_lds_dwordx4 v136, s[60:61]
	s_add_i32 m0, s20, 0xe000
	s_nop 0
	s_add_u32 s98, s60, s6
	s_addc_u32 s99, s61, s7
	global_load_lds_dwordx4 v136, s[98:99]
	s_waitcnt vmcnt(8)
	s_waitcnt lgkmcnt(0)
	s_barrier
	s_setprio 1
	s_waitcnt lgkmcnt(0)
	v_mfma_f32_16x16x32_bf16 v[124:127], v[128:131], v[174:177], v[124:127]
	v_mfma_f32_16x16x32_bf16 v[120:123], v[146:149], v[174:177], v[120:123]
	v_mfma_f32_16x16x32_bf16 v[116:119], v[128:131], v[182:185], v[116:119]
	v_mfma_f32_16x16x32_bf16 v[112:115], v[146:149], v[182:185], v[112:115]
	v_mfma_f32_16x16x32_bf16 v[108:111], v[128:131], v[190:193], v[108:111]
	v_mfma_f32_16x16x32_bf16 v[104:107], v[146:149], v[190:193], v[104:107]
	v_mfma_f32_16x16x32_bf16 v[100:103], v[128:131], v[198:201], v[100:103]
	v_mfma_f32_16x16x32_bf16 v[96:99], v[146:149], v[198:201], v[96:99]
	v_mfma_f32_16x16x32_bf16 v[124:127], v[142:145], v[178:181], v[124:127]
	v_mfma_f32_16x16x32_bf16 v[120:123], v[154:157], v[178:181], v[120:123]
	v_mfma_f32_16x16x32_bf16 v[116:119], v[142:145], v[186:189], v[116:119]
	v_mfma_f32_16x16x32_bf16 v[112:115], v[154:157], v[186:189], v[112:115]
	v_mfma_f32_16x16x32_bf16 v[108:111], v[142:145], v[194:197], v[108:111]
	v_mfma_f32_16x16x32_bf16 v[104:107], v[154:157], v[194:197], v[104:107]
	v_mfma_f32_16x16x32_bf16 v[100:103], v[142:145], v[202:205], v[100:103]
	v_mfma_f32_16x16x32_bf16 v[96:99], v[154:157], v[202:205], v[96:99]
	s_setprio 0
	s_setprio 1
	v_mfma_f32_16x16x32_bf16 v[92:95], v[158:161], v[174:177], v[92:95]
	v_mfma_f32_16x16x32_bf16 v[88:91], v[166:169], v[174:177], v[88:91]
	v_mfma_f32_16x16x32_bf16 v[84:87], v[158:161], v[182:185], v[84:87]
	v_mfma_f32_16x16x32_bf16 v[80:83], v[166:169], v[182:185], v[80:83]
	v_mfma_f32_16x16x32_bf16 v[76:79], v[158:161], v[190:193], v[76:79]
	v_mfma_f32_16x16x32_bf16 v[72:75], v[166:169], v[190:193], v[72:75]
	v_mfma_f32_16x16x32_bf16 v[68:71], v[158:161], v[198:201], v[68:71]
	v_mfma_f32_16x16x32_bf16 v[64:67], v[166:169], v[198:201], v[64:67]
	v_mfma_f32_16x16x32_bf16 v[92:95], v[162:165], v[178:181], v[92:95]
	v_mfma_f32_16x16x32_bf16 v[88:91], v[170:173], v[178:181], v[88:91]
	v_mfma_f32_16x16x32_bf16 v[84:87], v[162:165], v[186:189], v[84:87]
	v_mfma_f32_16x16x32_bf16 v[80:83], v[170:173], v[186:189], v[80:83]
	s_setprio 2
	s_barrier
	v_mfma_f32_16x16x32_bf16 v[76:79], v[162:165], v[194:197], v[76:79]
	v_mfma_f32_16x16x32_bf16 v[72:75], v[170:173], v[194:197], v[72:75]
	v_mfma_f32_16x16x32_bf16 v[68:71], v[162:165], v[202:205], v[68:71]
	v_mfma_f32_16x16x32_bf16 v[64:67], v[170:173], v[202:205], v[64:67]
	s_setprio 0
	s_add_i32 s50, s72, s14
	s_mov_b32 m0, s50
	ds_read_b128 v[174:177], v153 offset:16384
	ds_read_b128 v[178:181], v153 offset:17408
	ds_read_b128 v[182:185], v153 offset:18432
	ds_read_b128 v[186:189], v153 offset:19456
	ds_read_b128 v[190:193], v153 offset:20480
	ds_read_b128 v[194:197], v153 offset:21504
	ds_read_b128 v[198:201], v153 offset:22528
	ds_read_b128 v[202:205], v153 offset:23552
	global_load_lds_dwordx4 v134, s[78:79]
	s_add_i32 m0, s50, 0x2000
	s_add_i32 s50, s73, s14
	s_add_u32 s98, s78, s6
	s_addc_u32 s99, s79, s7
	global_load_lds_dwordx4 v134, s[98:99]
	s_mov_b32 m0, s50
	s_nop 0
	s_add_u32 s98, s78, s8
	s_addc_u32 s99, s79, s9
	global_load_lds_dwordx4 v134, s[98:99]
	s_add_i32 m0, s50, 0x2000
	s_nop 0
	s_add_u32 s98, s78, s10
	s_addc_u32 s99, s79, s11
	global_load_lds_dwordx4 v134, s[98:99]
	s_mov_b32 m0, s20
	s_nop 0
	global_load_lds_dwordx4 v132, s[76:77]
	s_mov_b32 m0, s21
	s_nop 0
	s_add_u32 s98, s76, s6
	s_addc_u32 s99, s77, s7
	global_load_lds_dwordx4 v132, s[98:99]
	s_waitcnt vmcnt(8)
	s_waitcnt lgkmcnt(0)
	s_barrier
	s_setprio 1
	s_waitcnt lgkmcnt(0)
	v_mfma_f32_16x16x32_bf16 v[60:63], v[128:131], v[174:177], v[60:63]
	v_mfma_f32_16x16x32_bf16 v[56:59], v[146:149], v[174:177], v[56:59]
	v_mfma_f32_16x16x32_bf16 v[52:55], v[128:131], v[182:185], v[52:55]
	v_mfma_f32_16x16x32_bf16 v[48:51], v[146:149], v[182:185], v[48:51]
	v_mfma_f32_16x16x32_bf16 v[44:47], v[128:131], v[190:193], v[44:47]
	v_mfma_f32_16x16x32_bf16 v[40:43], v[146:149], v[190:193], v[40:43]
	v_mfma_f32_16x16x32_bf16 v[36:39], v[128:131], v[198:201], v[36:39]
	v_mfma_f32_16x16x32_bf16 v[32:35], v[146:149], v[198:201], v[32:35]
	v_mfma_f32_16x16x32_bf16 v[60:63], v[142:145], v[178:181], v[60:63]
	v_mfma_f32_16x16x32_bf16 v[56:59], v[154:157], v[178:181], v[56:59]
	v_mfma_f32_16x16x32_bf16 v[52:55], v[142:145], v[186:189], v[52:55]
	v_mfma_f32_16x16x32_bf16 v[48:51], v[154:157], v[186:189], v[48:51]
	v_mfma_f32_16x16x32_bf16 v[44:47], v[142:145], v[194:197], v[44:47]
	v_mfma_f32_16x16x32_bf16 v[40:43], v[154:157], v[194:197], v[40:43]
	v_mfma_f32_16x16x32_bf16 v[36:39], v[142:145], v[202:205], v[36:39]
	v_mfma_f32_16x16x32_bf16 v[32:35], v[154:157], v[202:205], v[32:35]
	s_setprio 0
	s_setprio 1
	v_mfma_f32_16x16x32_bf16 v[28:31], v[158:161], v[174:177], v[28:31]
	v_mfma_f32_16x16x32_bf16 v[24:27], v[166:169], v[174:177], v[24:27]
	v_mfma_f32_16x16x32_bf16 v[20:23], v[158:161], v[182:185], v[20:23]
	v_mfma_f32_16x16x32_bf16 v[16:19], v[166:169], v[182:185], v[16:19]
	v_mfma_f32_16x16x32_bf16 v[12:15], v[158:161], v[190:193], v[12:15]
	v_mfma_f32_16x16x32_bf16 v[8:11], v[166:169], v[190:193], v[8:11]
	v_mfma_f32_16x16x32_bf16 v[4:7], v[158:161], v[198:201], v[4:7]
	v_mfma_f32_16x16x32_bf16 v[0:3], v[166:169], v[198:201], v[0:3]
	v_mfma_f32_16x16x32_bf16 v[28:31], v[162:165], v[178:181], v[28:31]
	v_mfma_f32_16x16x32_bf16 v[24:27], v[170:173], v[178:181], v[24:27]
	v_mfma_f32_16x16x32_bf16 v[20:23], v[162:165], v[186:189], v[20:23]
	v_mfma_f32_16x16x32_bf16 v[16:19], v[170:173], v[186:189], v[16:19]
	s_setprio 2
	s_barrier
	v_mfma_f32_16x16x32_bf16 v[12:15], v[162:165], v[194:197], v[12:15]
	v_mfma_f32_16x16x32_bf16 v[8:11], v[170:173], v[194:197], v[8:11]
	v_mfma_f32_16x16x32_bf16 v[4:7], v[162:165], v[202:205], v[4:7]
	v_mfma_f32_16x16x32_bf16 v[0:3], v[170:173], v[202:205], v[0:3]
	s_setprio 0
	s_add_i32 s50, 0, 0x18000
	s_add_i32 s51, 0, 0x1c000
	v_add_u32_e32 v154, s50, v150
	v_add_u32_e32 v170, s51, v150
	ds_read_b128 v[128:131], v154
	ds_read_b128 v[142:145], v154 offset:1024
	ds_read_b128 v[146:149], v154 offset:2048
	ds_read_b128 v[154:157], v154 offset:3072
	ds_read_b128 v[158:161], v170
	ds_read_b128 v[162:165], v170 offset:1024
	ds_read_b128 v[166:169], v170 offset:2048
	ds_read_b128 v[170:173], v170 offset:3072
	s_mov_b32 m0, s33
	ds_read_b128 v[174:177], v153 offset:32768
	ds_read_b128 v[178:181], v153 offset:33792
	ds_read_b128 v[182:185], v153 offset:34816
	ds_read_b128 v[186:189], v153 offset:35840
	ds_read_b128 v[190:193], v153 offset:36864
	ds_read_b128 v[194:197], v153 offset:37888
	ds_read_b128 v[198:201], v153 offset:38912
	ds_read_b128 v[202:205], v153 offset:39936
	s_add_u32 s98, s76, s8
	s_addc_u32 s99, s77, s9
	global_load_lds_dwordx4 v132, s[98:99]
	s_mov_b32 m0, s64
	s_nop 0
	s_add_u32 s98, s76, s10
	s_addc_u32 s99, s77, s11
	global_load_lds_dwordx4 v132, s[98:99]
	s_waitcnt vmcnt(8)
	s_waitcnt lgkmcnt(0)
	s_barrier
	s_setprio 1
	s_waitcnt lgkmcnt(0)
	v_mfma_f32_16x16x32_bf16 v[124:127], v[128:131], v[174:177], v[124:127]
	v_mfma_f32_16x16x32_bf16 v[120:123], v[146:149], v[174:177], v[120:123]
	v_mfma_f32_16x16x32_bf16 v[116:119], v[128:131], v[182:185], v[116:119]
	v_mfma_f32_16x16x32_bf16 v[112:115], v[146:149], v[182:185], v[112:115]
	v_mfma_f32_16x16x32_bf16 v[108:111], v[128:131], v[190:193], v[108:111]
	v_mfma_f32_16x16x32_bf16 v[104:107], v[146:149], v[190:193], v[104:107]
	v_mfma_f32_16x16x32_bf16 v[100:103], v[128:131], v[198:201], v[100:103]
	v_mfma_f32_16x16x32_bf16 v[96:99], v[146:149], v[198:201], v[96:99]
	v_mfma_f32_16x16x32_bf16 v[124:127], v[142:145], v[178:181], v[124:127]
	v_mfma_f32_16x16x32_bf16 v[120:123], v[154:157], v[178:181], v[120:123]
	v_mfma_f32_16x16x32_bf16 v[116:119], v[142:145], v[186:189], v[116:119]
	v_mfma_f32_16x16x32_bf16 v[112:115], v[154:157], v[186:189], v[112:115]
	v_mfma_f32_16x16x32_bf16 v[108:111], v[142:145], v[194:197], v[108:111]
	v_mfma_f32_16x16x32_bf16 v[104:107], v[154:157], v[194:197], v[104:107]
	v_mfma_f32_16x16x32_bf16 v[100:103], v[142:145], v[202:205], v[100:103]
	v_mfma_f32_16x16x32_bf16 v[96:99], v[154:157], v[202:205], v[96:99]
	s_setprio 0
	s_setprio 1
	v_mfma_f32_16x16x32_bf16 v[92:95], v[158:161], v[174:177], v[92:95]
	v_mfma_f32_16x16x32_bf16 v[88:91], v[166:169], v[174:177], v[88:91]
	v_mfma_f32_16x16x32_bf16 v[84:87], v[158:161], v[182:185], v[84:87]
	v_mfma_f32_16x16x32_bf16 v[80:83], v[166:169], v[182:185], v[80:83]
	v_mfma_f32_16x16x32_bf16 v[76:79], v[158:161], v[190:193], v[76:79]
	v_mfma_f32_16x16x32_bf16 v[72:75], v[166:169], v[190:193], v[72:75]
	v_mfma_f32_16x16x32_bf16 v[68:71], v[158:161], v[198:201], v[68:71]
	v_mfma_f32_16x16x32_bf16 v[64:67], v[166:169], v[198:201], v[64:67]
	v_mfma_f32_16x16x32_bf16 v[92:95], v[162:165], v[178:181], v[92:95]
	v_mfma_f32_16x16x32_bf16 v[88:91], v[170:173], v[178:181], v[88:91]
	v_mfma_f32_16x16x32_bf16 v[84:87], v[162:165], v[186:189], v[84:87]
	v_mfma_f32_16x16x32_bf16 v[80:83], v[170:173], v[186:189], v[80:83]
	s_setprio 2
	s_barrier
	v_mfma_f32_16x16x32_bf16 v[76:79], v[162:165], v[194:197], v[76:79]
	v_mfma_f32_16x16x32_bf16 v[72:75], v[170:173], v[194:197], v[72:75]
	v_mfma_f32_16x16x32_bf16 v[68:71], v[162:165], v[202:205], v[68:71]
	v_mfma_f32_16x16x32_bf16 v[64:67], v[170:173], v[202:205], v[64:67]
	s_setprio 0
	s_add_i32 s50, s50, s14
	s_mov_b32 m0, s50
	ds_read_b128 v[174:177], v153 offset:49152
	ds_read_b128 v[178:181], v153 offset:50176
	ds_read_b128 v[182:185], v153 offset:51200
	ds_read_b128 v[186:189], v153 offset:52224
	ds_read_b128 v[190:193], v153 offset:53248
	ds_read_b128 v[194:197], v153 offset:54272
	ds_read_b128 v[198:201], v153 offset:55296
	ds_read_b128 v[202:205], v153 offset:56320
	s_add_u32 s98, s78, s24
	s_addc_u32 s99, s79, s25
	global_load_lds_dwordx4 v134, s[98:99]
	s_add_i32 m0, s50, 0x2000
	s_add_i32 s50, s51, s14
	s_add_u32 s98, s78, s34
	s_addc_u32 s99, s79, s35
	global_load_lds_dwordx4 v134, s[98:99]
	s_mov_b32 m0, s50
	s_add_u32 s98, s78, s36
	s_addc_u32 s99, s79, s37
	global_load_lds_dwordx4 v134, s[98:99]
	s_add_i32 m0, s50, 0x2000
	s_nop 0
	s_add_u32 s98, s78, s38
	s_addc_u32 s99, s79, s39
	global_load_lds_dwordx4 v134, s[98:99]
	s_mov_b32 m0, s66
	s_nop 0
	s_add_u32 s98, s76, s24
	s_addc_u32 s99, s77, s25
	global_load_lds_dwordx4 v132, s[98:99]
	s_mov_b32 m0, s67
	s_nop 0
	s_add_u32 s98, s76, s34
	s_addc_u32 s99, s77, s35
	global_load_lds_dwordx4 v132, s[98:99]
	s_waitcnt vmcnt(8)
	s_waitcnt lgkmcnt(0)
	s_barrier
	s_setprio 1
	s_waitcnt lgkmcnt(0)
	v_mfma_f32_16x16x32_bf16 v[60:63], v[128:131], v[174:177], v[60:63]
	v_mfma_f32_16x16x32_bf16 v[56:59], v[146:149], v[174:177], v[56:59]
	v_mfma_f32_16x16x32_bf16 v[52:55], v[128:131], v[182:185], v[52:55]
	v_mfma_f32_16x16x32_bf16 v[48:51], v[146:149], v[182:185], v[48:51]
	v_mfma_f32_16x16x32_bf16 v[44:47], v[128:131], v[190:193], v[44:47]
	v_mfma_f32_16x16x32_bf16 v[40:43], v[146:149], v[190:193], v[40:43]
	v_mfma_f32_16x16x32_bf16 v[36:39], v[128:131], v[198:201], v[36:39]
	v_mfma_f32_16x16x32_bf16 v[32:35], v[146:149], v[198:201], v[32:35]
	v_mfma_f32_16x16x32_bf16 v[60:63], v[142:145], v[178:181], v[60:63]
	v_mfma_f32_16x16x32_bf16 v[56:59], v[154:157], v[178:181], v[56:59]
	v_mfma_f32_16x16x32_bf16 v[52:55], v[142:145], v[186:189], v[52:55]
	v_mfma_f32_16x16x32_bf16 v[48:51], v[154:157], v[186:189], v[48:51]
	v_mfma_f32_16x16x32_bf16 v[44:47], v[142:145], v[194:197], v[44:47]
	v_mfma_f32_16x16x32_bf16 v[40:43], v[154:157], v[194:197], v[40:43]
	v_mfma_f32_16x16x32_bf16 v[36:39], v[142:145], v[202:205], v[36:39]
	v_mfma_f32_16x16x32_bf16 v[32:35], v[154:157], v[202:205], v[32:35]
	s_setprio 0
	s_setprio 1
	v_mfma_f32_16x16x32_bf16 v[28:31], v[158:161], v[174:177], v[28:31]
	v_mfma_f32_16x16x32_bf16 v[24:27], v[166:169], v[174:177], v[24:27]
	v_mfma_f32_16x16x32_bf16 v[20:23], v[158:161], v[182:185], v[20:23]
	v_mfma_f32_16x16x32_bf16 v[16:19], v[166:169], v[182:185], v[16:19]
	v_mfma_f32_16x16x32_bf16 v[12:15], v[158:161], v[190:193], v[12:15]
	v_mfma_f32_16x16x32_bf16 v[8:11], v[166:169], v[190:193], v[8:11]
	v_mfma_f32_16x16x32_bf16 v[4:7], v[158:161], v[198:201], v[4:7]
	v_mfma_f32_16x16x32_bf16 v[0:3], v[166:169], v[198:201], v[0:3]
	v_mfma_f32_16x16x32_bf16 v[28:31], v[162:165], v[178:181], v[28:31]
	v_mfma_f32_16x16x32_bf16 v[24:27], v[170:173], v[178:181], v[24:27]
	v_mfma_f32_16x16x32_bf16 v[20:23], v[162:165], v[186:189], v[20:23]
	v_mfma_f32_16x16x32_bf16 v[16:19], v[170:173], v[186:189], v[16:19]
	s_setprio 2
	s_barrier
	v_mfma_f32_16x16x32_bf16 v[12:15], v[162:165], v[194:197], v[12:15]
	v_mfma_f32_16x16x32_bf16 v[8:11], v[170:173], v[194:197], v[8:11]
	v_mfma_f32_16x16x32_bf16 v[4:7], v[162:165], v[202:205], v[4:7]
	v_mfma_f32_16x16x32_bf16 v[0:3], v[170:173], v[202:205], v[0:3]
	s_setprio 0
	s_add_i32 s62, s62, 2
	s_add_u32 s74, s74, 0x100
	s_addc_u32 s75, s75, 0
	s_add_u32 s60, s60, 0x100
	s_addc_u32 s61, s61, 0
	s_cmp_gt_u32 s62, 61
	s_cbranch_scc0 .LBB0_627
	s_and_b64 vcc, exec, s[40:41]
	s_cbranch_vccz .LBB0_630
	s_barrier

.LBB0_800:
	ds_read_b128 v[128:131], v187
	ds_read_b128 v[132:135], v187 offset:1024
	ds_read_b128 v[136:139], v187 offset:2048
	ds_read_b128 v[140:143], v187 offset:3072
	ds_read_b128 v[144:147], v188
	ds_read_b128 v[148:151], v188 offset:1024
	ds_read_b128 v[152:155], v188 offset:2048
	ds_read_b128 v[156:159], v188 offset:3072
	s_add_u32 s9, s6, 0xfff80080
	s_addc_u32 s50, s7, -1
	s_cmp_eq_u32 s8, 28
	s_cselect_b32 vcc_hi, s5, s50
	s_cselect_b32 vcc_lo, s10, s9
	s_cselect_b32 s51, s11, s78
	s_cselect_b32 s50, s73, s75
	s_add_i32 m0, s65, 0xc000
	ds_read_b128 v[160:163], v189
	ds_read_b128 v[164:167], v189 offset:1024
	ds_read_b128 v[168:171], v189 offset:2048
	ds_read_b128 v[192:195], v189 offset:3072
	ds_read_b128 v[196:199], v189 offset:4096
	ds_read_b128 v[200:203], v189 offset:5120
	ds_read_b128 v[204:207], v189 offset:6144
	ds_read_b128 v[208:211], v189 offset:7168
	global_load_lds_dwordx4 v178, s[6:7]
	s_add_i32 m0, s65, 0xe000
	s_nop 0
	s_add_u32 s98, s6, s36
	s_addc_u32 s99, s7, s37
	global_load_lds_dwordx4 v178, s[98:99]
	s_waitcnt vmcnt(8)
	s_waitcnt lgkmcnt(0)
	s_barrier
	s_setprio 1
	s_waitcnt lgkmcnt(0)
	v_mfma_i32_16x16x64_i8 v[84:87], v[128:131], v[160:163], v[84:87]
	v_mfma_i32_16x16x64_i8 v[16:19], v[136:139], v[160:163], v[16:19]
	v_mfma_i32_16x16x64_i8 v[88:91], v[128:131], v[168:171], v[88:91]
	v_mfma_i32_16x16x64_i8 v[20:23], v[136:139], v[168:171], v[20:23]
	v_mfma_i32_16x16x64_i8 v[92:95], v[128:131], v[196:199], v[92:95]
	v_mfma_i32_16x16x64_i8 v[24:27], v[136:139], v[196:199], v[24:27]
	v_mfma_i32_16x16x64_i8 v[96:99], v[128:131], v[204:207], v[96:99]
	v_mfma_i32_16x16x64_i8 v[28:31], v[136:139], v[204:207], v[28:31]
	v_mfma_i32_16x16x64_i8 v[84:87], v[132:135], v[164:167], v[84:87]
	v_mfma_i32_16x16x64_i8 v[16:19], v[140:143], v[164:167], v[16:19]
	v_mfma_i32_16x16x64_i8 v[88:91], v[132:135], v[192:195], v[88:91]
	v_mfma_i32_16x16x64_i8 v[20:23], v[140:143], v[192:195], v[20:23]
	v_mfma_i32_16x16x64_i8 v[92:95], v[132:135], v[200:203], v[92:95]
	v_mfma_i32_16x16x64_i8 v[24:27], v[140:143], v[200:203], v[24:27]
	v_mfma_i32_16x16x64_i8 v[96:99], v[132:135], v[208:211], v[96:99]
	v_mfma_i32_16x16x64_i8 v[28:31], v[140:143], v[208:211], v[28:31]
	s_setprio 0
	s_setprio 1
	v_mfma_i32_16x16x64_i8 v[124:127], v[144:147], v[160:163], v[124:127]
	v_mfma_i32_16x16x64_i8 v[68:71], v[152:155], v[160:163], v[68:71]
	v_mfma_i32_16x16x64_i8 v[120:123], v[144:147], v[168:171], v[120:123]
	v_mfma_i32_16x16x64_i8 v[72:75], v[152:155], v[168:171], v[72:75]
	v_mfma_i32_16x16x64_i8 v[116:119], v[144:147], v[196:199], v[116:119]
	v_mfma_i32_16x16x64_i8 v[80:83], v[152:155], v[196:199], v[80:83]
	v_mfma_i32_16x16x64_i8 v[112:115], v[144:147], v[204:207], v[112:115]
	v_mfma_i32_16x16x64_i8 v[60:63], v[152:155], v[204:207], v[60:63]
	v_mfma_i32_16x16x64_i8 v[124:127], v[148:151], v[164:167], v[124:127]
	v_mfma_i32_16x16x64_i8 v[68:71], v[156:159], v[164:167], v[68:71]
	v_mfma_i32_16x16x64_i8 v[120:123], v[148:151], v[192:195], v[120:123]
	v_mfma_i32_16x16x64_i8 v[72:75], v[156:159], v[192:195], v[72:75]
	s_setprio 2
	s_barrier
	v_mfma_i32_16x16x64_i8 v[116:119], v[148:151], v[200:203], v[116:119]
	v_mfma_i32_16x16x64_i8 v[80:83], v[156:159], v[200:203], v[80:83]
	v_mfma_i32_16x16x64_i8 v[112:115], v[148:151], v[208:211], v[112:115]
	v_mfma_i32_16x16x64_i8 v[60:63], v[156:159], v[208:211], v[60:63]
	s_setprio 0
	s_add_i32 s9, s80, s33
	s_mov_b64 s[100:101], s[50:51]
	s_mov_b32 m0, s9
	ds_read_b128 v[160:163], v189 offset:16384
	ds_read_b128 v[164:167], v189 offset:17408
	ds_read_b128 v[168:171], v189 offset:18432
	ds_read_b128 v[192:195], v189 offset:19456
	ds_read_b128 v[196:199], v189 offset:20480
	ds_read_b128 v[200:203], v189 offset:21504
	ds_read_b128 v[204:207], v189 offset:22528
	ds_read_b128 v[208:211], v189 offset:23552
	global_load_lds_dwordx4 v174, s[50:51]
	s_add_i32 m0, s9, 0x2000
	s_add_i32 s9, s81, s33
	s_add_u32 s98, s50, s36
	s_addc_u32 s99, s51, s37
	global_load_lds_dwordx4 v174, s[98:99]
	s_mov_b32 m0, s9
	s_nop 0
	s_add_u32 s98, s50, s38
	s_addc_u32 s99, s51, s39
	global_load_lds_dwordx4 v174, s[98:99]
	s_add_i32 m0, s9, 0x2000
	s_nop 0
	s_add_u32 s98, s50, s40
	s_addc_u32 s99, s51, s41
	global_load_lds_dwordx4 v174, s[98:99]
	s_mov_b32 m0, s65
	s_nop 0
	global_load_lds_dwordx4 v172, vcc
	s_mov_b32 m0, s67
	s_nop 0
	s_add_u32 s98, vcc_lo, s36
	s_addc_u32 s99, vcc_hi, s37
	global_load_lds_dwordx4 v172, s[98:99]
	s_waitcnt vmcnt(8)
	s_waitcnt lgkmcnt(0)
	s_barrier
	s_setprio 1
	s_waitcnt lgkmcnt(0)
	v_mfma_i32_16x16x64_i8 v[48:51], v[128:131], v[160:163], v[48:51]
	v_mfma_i32_16x16x64_i8 v[0:3], v[136:139], v[160:163], v[0:3]
	v_mfma_i32_16x16x64_i8 v[52:55], v[128:131], v[168:171], v[52:55]
	v_mfma_i32_16x16x64_i8 v[4:7], v[136:139], v[168:171], v[4:7]
	v_mfma_i32_16x16x64_i8 v[56:59], v[128:131], v[196:199], v[56:59]
	v_mfma_i32_16x16x64_i8 v[8:11], v[136:139], v[196:199], v[8:11]
	v_mfma_i32_16x16x64_i8 v[64:67], v[128:131], v[204:207], v[64:67]
	v_mfma_i32_16x16x64_i8 v[12:15], v[136:139], v[204:207], v[12:15]
	v_mfma_i32_16x16x64_i8 v[48:51], v[132:135], v[164:167], v[48:51]
	v_mfma_i32_16x16x64_i8 v[0:3], v[140:143], v[164:167], v[0:3]
	v_mfma_i32_16x16x64_i8 v[52:55], v[132:135], v[192:195], v[52:55]
	v_mfma_i32_16x16x64_i8 v[4:7], v[140:143], v[192:195], v[4:7]
	v_mfma_i32_16x16x64_i8 v[56:59], v[132:135], v[200:203], v[56:59]
	v_mfma_i32_16x16x64_i8 v[8:11], v[140:143], v[200:203], v[8:11]
	v_mfma_i32_16x16x64_i8 v[64:67], v[132:135], v[208:211], v[64:67]
	v_mfma_i32_16x16x64_i8 v[12:15], v[140:143], v[208:211], v[12:15]
	s_setprio 0
	s_setprio 1
	v_mfma_i32_16x16x64_i8 v[108:111], v[144:147], v[160:163], v[108:111]
	v_mfma_i32_16x16x64_i8 v[44:47], v[152:155], v[160:163], v[44:47]
	v_mfma_i32_16x16x64_i8 v[104:107], v[144:147], v[168:171], v[104:107]
	v_mfma_i32_16x16x64_i8 v[40:43], v[152:155], v[168:171], v[40:43]
	v_mfma_i32_16x16x64_i8 v[100:103], v[144:147], v[196:199], v[100:103]
	v_mfma_i32_16x16x64_i8 v[32:35], v[152:155], v[196:199], v[32:35]
	v_mfma_i32_16x16x64_i8 v[76:79], v[144:147], v[204:207], v[76:79]
	v_mfma_i32_16x16x64_i8 v[36:39], v[152:155], v[204:207], v[36:39]
	v_mfma_i32_16x16x64_i8 v[108:111], v[148:151], v[164:167], v[108:111]
	v_mfma_i32_16x16x64_i8 v[44:47], v[156:159], v[164:167], v[44:47]
	v_mfma_i32_16x16x64_i8 v[104:107], v[148:151], v[192:195], v[104:107]
	v_mfma_i32_16x16x64_i8 v[40:43], v[156:159], v[192:195], v[40:43]
	s_setprio 2
	s_barrier
	v_mfma_i32_16x16x64_i8 v[100:103], v[148:151], v[200:203], v[100:103]
	v_mfma_i32_16x16x64_i8 v[32:35], v[156:159], v[200:203], v[32:35]
	v_mfma_i32_16x16x64_i8 v[76:79], v[148:151], v[208:211], v[76:79]
	v_mfma_i32_16x16x64_i8 v[36:39], v[156:159], v[208:211], v[36:39]
	s_setprio 0
	s_add_i32 s9, 0, 0x18000
	s_add_i32 s50, 0, 0x1c000
	v_add_u32_e32 v140, s9, v186
	v_add_u32_e32 v156, s50, v186
	ds_read_b128 v[128:131], v140
	ds_read_b128 v[132:135], v140 offset:1024
	ds_read_b128 v[136:139], v140 offset:2048
	ds_read_b128 v[140:143], v140 offset:3072
	ds_read_b128 v[144:147], v156
	ds_read_b128 v[148:151], v156 offset:1024
	ds_read_b128 v[152:155], v156 offset:2048
	ds_read_b128 v[156:159], v156 offset:3072
	s_mov_b32 m0, s71
	ds_read_b128 v[160:163], v189 offset:32768
	ds_read_b128 v[164:167], v189 offset:33792
	ds_read_b128 v[168:171], v189 offset:34816
	ds_read_b128 v[192:195], v189 offset:35840
	ds_read_b128 v[196:199], v189 offset:36864
	ds_read_b128 v[200:203], v189 offset:37888
	ds_read_b128 v[204:207], v189 offset:38912
	ds_read_b128 v[208:211], v189 offset:39936
	s_add_u32 s98, vcc_lo, s38
	s_addc_u32 s99, vcc_hi, s39
	global_load_lds_dwordx4 v172, s[98:99]
	s_mov_b32 m0, s82
	s_nop 0
	s_add_u32 s98, vcc_lo, s40
	s_addc_u32 s99, vcc_hi, s41
	global_load_lds_dwordx4 v172, s[98:99]
	s_waitcnt vmcnt(8)
	s_waitcnt lgkmcnt(0)
	s_barrier
	s_setprio 1
	s_waitcnt lgkmcnt(0)
	v_mfma_i32_16x16x64_i8 v[84:87], v[128:131], v[160:163], v[84:87]
	v_mfma_i32_16x16x64_i8 v[16:19], v[136:139], v[160:163], v[16:19]
	v_mfma_i32_16x16x64_i8 v[88:91], v[128:131], v[168:171], v[88:91]
	v_mfma_i32_16x16x64_i8 v[20:23], v[136:139], v[168:171], v[20:23]
	v_mfma_i32_16x16x64_i8 v[92:95], v[128:131], v[196:199], v[92:95]
	v_mfma_i32_16x16x64_i8 v[24:27], v[136:139], v[196:199], v[24:27]
	v_mfma_i32_16x16x64_i8 v[96:99], v[128:131], v[204:207], v[96:99]
	v_mfma_i32_16x16x64_i8 v[28:31], v[136:139], v[204:207], v[28:31]
	v_mfma_i32_16x16x64_i8 v[84:87], v[132:135], v[164:167], v[84:87]
	v_mfma_i32_16x16x64_i8 v[16:19], v[140:143], v[164:167], v[16:19]
	v_mfma_i32_16x16x64_i8 v[88:91], v[132:135], v[192:195], v[88:91]
	v_mfma_i32_16x16x64_i8 v[20:23], v[140:143], v[192:195], v[20:23]
	v_mfma_i32_16x16x64_i8 v[92:95], v[132:135], v[200:203], v[92:95]
	v_mfma_i32_16x16x64_i8 v[24:27], v[140:143], v[200:203], v[24:27]
	v_mfma_i32_16x16x64_i8 v[96:99], v[132:135], v[208:211], v[96:99]
	v_mfma_i32_16x16x64_i8 v[28:31], v[140:143], v[208:211], v[28:31]
	s_setprio 0
	s_setprio 1
	v_mfma_i32_16x16x64_i8 v[124:127], v[144:147], v[160:163], v[124:127]
	v_mfma_i32_16x16x64_i8 v[68:71], v[152:155], v[160:163], v[68:71]
	v_mfma_i32_16x16x64_i8 v[120:123], v[144:147], v[168:171], v[120:123]
	v_mfma_i32_16x16x64_i8 v[72:75], v[152:155], v[168:171], v[72:75]
	v_mfma_i32_16x16x64_i8 v[116:119], v[144:147], v[196:199], v[116:119]
	v_mfma_i32_16x16x64_i8 v[80:83], v[152:155], v[196:199], v[80:83]
	v_mfma_i32_16x16x64_i8 v[112:115], v[144:147], v[204:207], v[112:115]
	v_mfma_i32_16x16x64_i8 v[60:63], v[152:155], v[204:207], v[60:63]
	v_mfma_i32_16x16x64_i8 v[124:127], v[148:151], v[164:167], v[124:127]
	v_mfma_i32_16x16x64_i8 v[68:71], v[156:159], v[164:167], v[68:71]
	v_mfma_i32_16x16x64_i8 v[120:123], v[148:151], v[192:195], v[120:123]
	v_mfma_i32_16x16x64_i8 v[72:75], v[156:159], v[192:195], v[72:75]
	s_setprio 2
	s_barrier
	v_mfma_i32_16x16x64_i8 v[116:119], v[148:151], v[200:203], v[116:119]
	v_mfma_i32_16x16x64_i8 v[80:83], v[156:159], v[200:203], v[80:83]
	v_mfma_i32_16x16x64_i8 v[112:115], v[148:151], v[208:211], v[112:115]
	v_mfma_i32_16x16x64_i8 v[60:63], v[156:159], v[208:211], v[60:63]
	s_setprio 0
	s_add_i32 s9, s9, s33
	s_mov_b32 m0, s9
	ds_read_b128 v[160:163], v189 offset:49152
	ds_read_b128 v[164:167], v189 offset:50176
	ds_read_b128 v[168:171], v189 offset:51200
	ds_read_b128 v[192:195], v189 offset:52224
	ds_read_b128 v[196:199], v189 offset:53248
	ds_read_b128 v[200:203], v189 offset:54272
	ds_read_b128 v[204:207], v189 offset:55296
	ds_read_b128 v[208:211], v189 offset:56320
	s_add_u32 s98, s100, s44
	s_addc_u32 s99, s101, s45
	global_load_lds_dwordx4 v174, s[98:99]
	s_add_i32 m0, s9, 0x2000
	s_add_i32 s9, s50, s33
	s_add_u32 s98, s100, s46
	s_addc_u32 s99, s101, s47
	global_load_lds_dwordx4 v174, s[98:99]
	s_mov_b32 m0, s9
	s_add_u32 s98, s100, s48
	s_addc_u32 s99, s101, s49
	global_load_lds_dwordx4 v174, s[98:99]
	s_add_i32 m0, s9, 0x2000
	s_nop 0
	s_add_u32 s98, s100, s52
	s_addc_u32 s99, s101, s53
	global_load_lds_dwordx4 v174, s[98:99]
	s_mov_b32 m0, s90
	s_nop 0
	s_add_u32 s98, vcc_lo, s44
	s_addc_u32 s99, vcc_hi, s45
	global_load_lds_dwordx4 v172, s[98:99]
	s_mov_b32 m0, s91
	s_nop 0
	s_add_u32 s98, vcc_lo, s46
	s_addc_u32 s99, vcc_hi, s47
	global_load_lds_dwordx4 v172, s[98:99]
	s_waitcnt vmcnt(8)
	s_waitcnt lgkmcnt(0)
	s_barrier
	s_setprio 1
	s_waitcnt lgkmcnt(0)
	v_mfma_i32_16x16x64_i8 v[48:51], v[128:131], v[160:163], v[48:51]
	v_mfma_i32_16x16x64_i8 v[0:3], v[136:139], v[160:163], v[0:3]
	v_mfma_i32_16x16x64_i8 v[52:55], v[128:131], v[168:171], v[52:55]
	v_mfma_i32_16x16x64_i8 v[4:7], v[136:139], v[168:171], v[4:7]
	v_mfma_i32_16x16x64_i8 v[56:59], v[128:131], v[196:199], v[56:59]
	v_mfma_i32_16x16x64_i8 v[8:11], v[136:139], v[196:199], v[8:11]
	v_mfma_i32_16x16x64_i8 v[64:67], v[128:131], v[204:207], v[64:67]
	v_mfma_i32_16x16x64_i8 v[12:15], v[136:139], v[204:207], v[12:15]
	v_mfma_i32_16x16x64_i8 v[48:51], v[132:135], v[164:167], v[48:51]
	v_mfma_i32_16x16x64_i8 v[0:3], v[140:143], v[164:167], v[0:3]
	v_mfma_i32_16x16x64_i8 v[52:55], v[132:135], v[192:195], v[52:55]
	v_mfma_i32_16x16x64_i8 v[4:7], v[140:143], v[192:195], v[4:7]
	v_mfma_i32_16x16x64_i8 v[56:59], v[132:135], v[200:203], v[56:59]
	v_mfma_i32_16x16x64_i8 v[8:11], v[140:143], v[200:203], v[8:11]
	v_mfma_i32_16x16x64_i8 v[64:67], v[132:135], v[208:211], v[64:67]
	v_mfma_i32_16x16x64_i8 v[12:15], v[140:143], v[208:211], v[12:15]
	s_setprio 0
	s_setprio 1
	v_mfma_i32_16x16x64_i8 v[108:111], v[144:147], v[160:163], v[108:111]
	v_mfma_i32_16x16x64_i8 v[44:47], v[152:155], v[160:163], v[44:47]
	v_mfma_i32_16x16x64_i8 v[104:107], v[144:147], v[168:171], v[104:107]
	v_mfma_i32_16x16x64_i8 v[40:43], v[152:155], v[168:171], v[40:43]
	v_mfma_i32_16x16x64_i8 v[100:103], v[144:147], v[196:199], v[100:103]
	v_mfma_i32_16x16x64_i8 v[32:35], v[152:155], v[196:199], v[32:35]
	v_mfma_i32_16x16x64_i8 v[76:79], v[144:147], v[204:207], v[76:79]
	v_mfma_i32_16x16x64_i8 v[36:39], v[152:155], v[204:207], v[36:39]
	v_mfma_i32_16x16x64_i8 v[108:111], v[148:151], v[164:167], v[108:111]
	v_mfma_i32_16x16x64_i8 v[44:47], v[156:159], v[164:167], v[44:47]
	v_mfma_i32_16x16x64_i8 v[104:107], v[148:151], v[192:195], v[104:107]
	v_mfma_i32_16x16x64_i8 v[40:43], v[156:159], v[192:195], v[40:43]
	s_setprio 2
	s_barrier
	v_mfma_i32_16x16x64_i8 v[100:103], v[148:151], v[200:203], v[100:103]
	v_mfma_i32_16x16x64_i8 v[32:35], v[156:159], v[200:203], v[32:35]
	v_mfma_i32_16x16x64_i8 v[76:79], v[148:151], v[208:211], v[76:79]
	v_mfma_i32_16x16x64_i8 v[36:39], v[156:159], v[208:211], v[36:39]
	s_setprio 0
	s_add_i32 s8, s8, 2
	s_add_u32 s75, s75, 0x100
	s_addc_u32 s78, s78, 0
	s_add_u32 s6, s6, 0x100
	s_addc_u32 s7, s7, 0
	s_cmp_gt_u32 s8, 29
	s_cbranch_scc0 .LBB0_800
	s_and_b64 vcc, exec, s[54:55]
	s_cbranch_vccz .LBB0_803
	s_barrier

.LBB0_1034:
	ds_read_b128 v[138:141], v151
	ds_read_b128 v[142:145], v151 offset:1024
	ds_read_b128 v[146:149], v151 offset:2048
	ds_read_b128 v[154:157], v151 offset:3072
	ds_read_b128 v[158:161], v152
	ds_read_b128 v[162:165], v152 offset:1024
	ds_read_b128 v[166:169], v152 offset:2048
	ds_read_b128 v[170:173], v152 offset:3072
	s_add_u32 s47, s44, 0xffd50080
	s_addc_u32 s64, s45, -1
	s_cmpk_eq_i32 s46, 0xa8
	s_cselect_b32 s65, s5, s64
	s_cselect_b32 s64, s4, s47
	s_cselect_b32 s67, s43, s63
	s_cselect_b32 s66, s42, s62
	s_add_i32 m0, s25, 0xc000
	ds_read_b128 v[174:177], v153
	ds_read_b128 v[178:181], v153 offset:1024
	ds_read_b128 v[182:185], v153 offset:2048
	ds_read_b128 v[186:189], v153 offset:3072
	ds_read_b128 v[190:193], v153 offset:4096
	ds_read_b128 v[194:197], v153 offset:5120
	ds_read_b128 v[198:201], v153 offset:6144
	ds_read_b128 v[202:205], v153 offset:7168
	global_load_lds_dwordx4 v132, s[44:45]
	s_add_i32 m0, s25, 0xe000
	s_nop 0
	s_add_u32 s98, s44, s0
	s_addc_u32 s99, s45, s1
	global_load_lds_dwordx4 v132, s[98:99]
	s_waitcnt vmcnt(8)
	s_waitcnt lgkmcnt(0)
	s_barrier
	s_setprio 1
	s_waitcnt lgkmcnt(0)
	v_mfma_f32_16x16x32_bf16 v[124:127], v[138:141], v[174:177], v[124:127]
	v_mfma_f32_16x16x32_bf16 v[120:123], v[146:149], v[174:177], v[120:123]
	v_mfma_f32_16x16x32_bf16 v[116:119], v[138:141], v[182:185], v[116:119]
	v_mfma_f32_16x16x32_bf16 v[112:115], v[146:149], v[182:185], v[112:115]
	v_mfma_f32_16x16x32_bf16 v[108:111], v[138:141], v[190:193], v[108:111]
	v_mfma_f32_16x16x32_bf16 v[104:107], v[146:149], v[190:193], v[104:107]
	v_mfma_f32_16x16x32_bf16 v[100:103], v[138:141], v[198:201], v[100:103]
	v_mfma_f32_16x16x32_bf16 v[96:99], v[146:149], v[198:201], v[96:99]
	v_mfma_f32_16x16x32_bf16 v[124:127], v[142:145], v[178:181], v[124:127]
	v_mfma_f32_16x16x32_bf16 v[120:123], v[154:157], v[178:181], v[120:123]
	v_mfma_f32_16x16x32_bf16 v[116:119], v[142:145], v[186:189], v[116:119]
	v_mfma_f32_16x16x32_bf16 v[112:115], v[154:157], v[186:189], v[112:115]
	v_mfma_f32_16x16x32_bf16 v[108:111], v[142:145], v[194:197], v[108:111]
	v_mfma_f32_16x16x32_bf16 v[104:107], v[154:157], v[194:197], v[104:107]
	v_mfma_f32_16x16x32_bf16 v[100:103], v[142:145], v[202:205], v[100:103]
	v_mfma_f32_16x16x32_bf16 v[96:99], v[154:157], v[202:205], v[96:99]
	s_setprio 0
	s_setprio 1
	v_mfma_f32_16x16x32_bf16 v[92:95], v[158:161], v[174:177], v[92:95]
	v_mfma_f32_16x16x32_bf16 v[88:91], v[166:169], v[174:177], v[88:91]
	v_mfma_f32_16x16x32_bf16 v[84:87], v[158:161], v[182:185], v[84:87]
	v_mfma_f32_16x16x32_bf16 v[80:83], v[166:169], v[182:185], v[80:83]
	v_mfma_f32_16x16x32_bf16 v[76:79], v[158:161], v[190:193], v[76:79]
	v_mfma_f32_16x16x32_bf16 v[72:75], v[166:169], v[190:193], v[72:75]
	v_mfma_f32_16x16x32_bf16 v[68:71], v[158:161], v[198:201], v[68:71]
	v_mfma_f32_16x16x32_bf16 v[64:67], v[166:169], v[198:201], v[64:67]
	v_mfma_f32_16x16x32_bf16 v[92:95], v[162:165], v[178:181], v[92:95]
	v_mfma_f32_16x16x32_bf16 v[88:91], v[170:173], v[178:181], v[88:91]
	v_mfma_f32_16x16x32_bf16 v[84:87], v[162:165], v[186:189], v[84:87]
	v_mfma_f32_16x16x32_bf16 v[80:83], v[170:173], v[186:189], v[80:83]
	s_setprio 2
	s_barrier
	v_mfma_f32_16x16x32_bf16 v[76:79], v[162:165], v[194:197], v[76:79]
	v_mfma_f32_16x16x32_bf16 v[72:75], v[170:173], v[194:197], v[72:75]
	v_mfma_f32_16x16x32_bf16 v[68:71], v[162:165], v[202:205], v[68:71]
	v_mfma_f32_16x16x32_bf16 v[64:67], v[170:173], v[202:205], v[64:67]
	s_setprio 0
	s_add_i32 s47, s56, s24
	s_mov_b32 m0, s47
	ds_read_b128 v[174:177], v153 offset:16384
	ds_read_b128 v[178:181], v153 offset:17408
	ds_read_b128 v[182:185], v153 offset:18432
	ds_read_b128 v[186:189], v153 offset:19456
	ds_read_b128 v[190:193], v153 offset:20480
	ds_read_b128 v[194:197], v153 offset:21504
	ds_read_b128 v[198:201], v153 offset:22528
	ds_read_b128 v[202:205], v153 offset:23552
	global_load_lds_dwordx4 v130, s[66:67]
	s_add_i32 m0, s47, 0x2000
	s_add_i32 s47, s57, s24
	s_add_u32 s98, s66, s0
	s_addc_u32 s99, s67, s1
	global_load_lds_dwordx4 v130, s[98:99]
	s_mov_b32 m0, s47
	s_nop 0
	s_add_u32 s98, s66, s6
	s_addc_u32 s99, s67, s7
	global_load_lds_dwordx4 v130, s[98:99]
	s_add_i32 m0, s47, 0x2000
	s_nop 0
	s_add_u32 s98, s66, s8
	s_addc_u32 s99, s67, s9
	global_load_lds_dwordx4 v130, s[98:99]
	s_mov_b64 s[100:101], s[64:65]
	s_mov_b32 m0, s25
	s_nop 0
	global_load_lds_dwordx4 v128, s[64:65]
	s_mov_b32 m0, s33
	s_nop 0
	s_add_u32 s98, s64, s0
	s_addc_u32 s99, s65, s1
	global_load_lds_dwordx4 v128, s[98:99]
	s_waitcnt vmcnt(8)
	s_waitcnt lgkmcnt(0)
	s_barrier
	s_setprio 1
	s_waitcnt lgkmcnt(0)
	v_mfma_f32_16x16x32_bf16 v[60:63], v[138:141], v[174:177], v[60:63]
	v_mfma_f32_16x16x32_bf16 v[56:59], v[146:149], v[174:177], v[56:59]
	v_mfma_f32_16x16x32_bf16 v[52:55], v[138:141], v[182:185], v[52:55]
	v_mfma_f32_16x16x32_bf16 v[48:51], v[146:149], v[182:185], v[48:51]
	v_mfma_f32_16x16x32_bf16 v[44:47], v[138:141], v[190:193], v[44:47]
	v_mfma_f32_16x16x32_bf16 v[40:43], v[146:149], v[190:193], v[40:43]
	v_mfma_f32_16x16x32_bf16 v[36:39], v[138:141], v[198:201], v[36:39]
	v_mfma_f32_16x16x32_bf16 v[32:35], v[146:149], v[198:201], v[32:35]
	v_mfma_f32_16x16x32_bf16 v[60:63], v[142:145], v[178:181], v[60:63]
	v_mfma_f32_16x16x32_bf16 v[56:59], v[154:157], v[178:181], v[56:59]
	v_mfma_f32_16x16x32_bf16 v[52:55], v[142:145], v[186:189], v[52:55]
	v_mfma_f32_16x16x32_bf16 v[48:51], v[154:157], v[186:189], v[48:51]
	v_mfma_f32_16x16x32_bf16 v[44:47], v[142:145], v[194:197], v[44:47]
	v_mfma_f32_16x16x32_bf16 v[40:43], v[154:157], v[194:197], v[40:43]
	v_mfma_f32_16x16x32_bf16 v[36:39], v[142:145], v[202:205], v[36:39]
	v_mfma_f32_16x16x32_bf16 v[32:35], v[154:157], v[202:205], v[32:35]
	s_setprio 0
	s_setprio 1
	v_mfma_f32_16x16x32_bf16 v[28:31], v[158:161], v[174:177], v[28:31]
	v_mfma_f32_16x16x32_bf16 v[24:27], v[166:169], v[174:177], v[24:27]
	v_mfma_f32_16x16x32_bf16 v[20:23], v[158:161], v[182:185], v[20:23]
	v_mfma_f32_16x16x32_bf16 v[16:19], v[166:169], v[182:185], v[16:19]
	v_mfma_f32_16x16x32_bf16 v[12:15], v[158:161], v[190:193], v[12:15]
	v_mfma_f32_16x16x32_bf16 v[8:11], v[166:169], v[190:193], v[8:11]
	v_mfma_f32_16x16x32_bf16 v[4:7], v[158:161], v[198:201], v[4:7]
	v_mfma_f32_16x16x32_bf16 v[0:3], v[166:169], v[198:201], v[0:3]
	v_mfma_f32_16x16x32_bf16 v[28:31], v[162:165], v[178:181], v[28:31]
	v_mfma_f32_16x16x32_bf16 v[24:27], v[170:173], v[178:181], v[24:27]
	v_mfma_f32_16x16x32_bf16 v[20:23], v[162:165], v[186:189], v[20:23]
	v_mfma_f32_16x16x32_bf16 v[16:19], v[170:173], v[186:189], v[16:19]
	s_setprio 2
	s_barrier
	v_mfma_f32_16x16x32_bf16 v[12:15], v[162:165], v[194:197], v[12:15]
	v_mfma_f32_16x16x32_bf16 v[8:11], v[170:173], v[194:197], v[8:11]
	v_mfma_f32_16x16x32_bf16 v[4:7], v[162:165], v[202:205], v[4:7]
	v_mfma_f32_16x16x32_bf16 v[0:3], v[170:173], v[202:205], v[0:3]
	s_setprio 0
	s_add_i32 s47, 0, 0x18000
	s_add_i32 s64, 0, 0x1c000
	v_add_u32_e32 v154, s47, v150
	v_add_u32_e32 v170, s64, v150
	ds_read_b128 v[138:141], v154
	ds_read_b128 v[142:145], v154 offset:1024
	ds_read_b128 v[146:149], v154 offset:2048
	ds_read_b128 v[154:157], v154 offset:3072
	ds_read_b128 v[158:161], v170
	ds_read_b128 v[162:165], v170 offset:1024
	ds_read_b128 v[166:169], v170 offset:2048
	ds_read_b128 v[170:173], v170 offset:3072
	s_mov_b32 m0, s48
	ds_read_b128 v[174:177], v153 offset:32768
	ds_read_b128 v[178:181], v153 offset:33792
	ds_read_b128 v[182:185], v153 offset:34816
	ds_read_b128 v[186:189], v153 offset:35840
	ds_read_b128 v[190:193], v153 offset:36864
	ds_read_b128 v[194:197], v153 offset:37888
	ds_read_b128 v[198:201], v153 offset:38912
	ds_read_b128 v[202:205], v153 offset:39936
	s_add_u32 s98, s100, s6
	s_addc_u32 s99, s101, s7
	global_load_lds_dwordx4 v128, s[98:99]
	s_mov_b32 m0, s49
	s_nop 0
	s_add_u32 s98, s100, s8
	s_addc_u32 s99, s101, s9
	global_load_lds_dwordx4 v128, s[98:99]
	s_waitcnt vmcnt(8)
	s_waitcnt lgkmcnt(0)
	s_barrier
	s_setprio 1
	s_waitcnt lgkmcnt(0)
	v_mfma_f32_16x16x32_bf16 v[124:127], v[138:141], v[174:177], v[124:127]
	v_mfma_f32_16x16x32_bf16 v[120:123], v[146:149], v[174:177], v[120:123]
	v_mfma_f32_16x16x32_bf16 v[116:119], v[138:141], v[182:185], v[116:119]
	v_mfma_f32_16x16x32_bf16 v[112:115], v[146:149], v[182:185], v[112:115]
	v_mfma_f32_16x16x32_bf16 v[108:111], v[138:141], v[190:193], v[108:111]
	v_mfma_f32_16x16x32_bf16 v[104:107], v[146:149], v[190:193], v[104:107]
	v_mfma_f32_16x16x32_bf16 v[100:103], v[138:141], v[198:201], v[100:103]
	v_mfma_f32_16x16x32_bf16 v[96:99], v[146:149], v[198:201], v[96:99]
	v_mfma_f32_16x16x32_bf16 v[124:127], v[142:145], v[178:181], v[124:127]
	v_mfma_f32_16x16x32_bf16 v[120:123], v[154:157], v[178:181], v[120:123]
	v_mfma_f32_16x16x32_bf16 v[116:119], v[142:145], v[186:189], v[116:119]
	v_mfma_f32_16x16x32_bf16 v[112:115], v[154:157], v[186:189], v[112:115]
	v_mfma_f32_16x16x32_bf16 v[108:111], v[142:145], v[194:197], v[108:111]
	v_mfma_f32_16x16x32_bf16 v[104:107], v[154:157], v[194:197], v[104:107]
	v_mfma_f32_16x16x32_bf16 v[100:103], v[142:145], v[202:205], v[100:103]
	v_mfma_f32_16x16x32_bf16 v[96:99], v[154:157], v[202:205], v[96:99]
	s_setprio 0
	s_setprio 1
	v_mfma_f32_16x16x32_bf16 v[92:95], v[158:161], v[174:177], v[92:95]
	v_mfma_f32_16x16x32_bf16 v[88:91], v[166:169], v[174:177], v[88:91]
	v_mfma_f32_16x16x32_bf16 v[84:87], v[158:161], v[182:185], v[84:87]
	v_mfma_f32_16x16x32_bf16 v[80:83], v[166:169], v[182:185], v[80:83]
	v_mfma_f32_16x16x32_bf16 v[76:79], v[158:161], v[190:193], v[76:79]
	v_mfma_f32_16x16x32_bf16 v[72:75], v[166:169], v[190:193], v[72:75]
	v_mfma_f32_16x16x32_bf16 v[68:71], v[158:161], v[198:201], v[68:71]
	v_mfma_f32_16x16x32_bf16 v[64:67], v[166:169], v[198:201], v[64:67]
	v_mfma_f32_16x16x32_bf16 v[92:95], v[162:165], v[178:181], v[92:95]
	v_mfma_f32_16x16x32_bf16 v[88:91], v[170:173], v[178:181], v[88:91]
	v_mfma_f32_16x16x32_bf16 v[84:87], v[162:165], v[186:189], v[84:87]
	v_mfma_f32_16x16x32_bf16 v[80:83], v[170:173], v[186:189], v[80:83]
	s_setprio 2
	s_barrier
	v_mfma_f32_16x16x32_bf16 v[76:79], v[162:165], v[194:197], v[76:79]
	v_mfma_f32_16x16x32_bf16 v[72:75], v[170:173], v[194:197], v[72:75]
	v_mfma_f32_16x16x32_bf16 v[68:71], v[162:165], v[202:205], v[68:71]
	v_mfma_f32_16x16x32_bf16 v[64:67], v[170:173], v[202:205], v[64:67]
	s_setprio 0
	s_add_i32 s47, s47, s24
	s_mov_b32 m0, s47
	ds_read_b128 v[174:177], v153 offset:49152
	ds_read_b128 v[178:181], v153 offset:50176
	ds_read_b128 v[182:185], v153 offset:51200
	ds_read_b128 v[186:189], v153 offset:52224
	ds_read_b128 v[190:193], v153 offset:53248
	ds_read_b128 v[194:197], v153 offset:54272
	ds_read_b128 v[198:201], v153 offset:55296
	ds_read_b128 v[202:205], v153 offset:56320
	s_add_u32 s98, s66, s16
	s_addc_u32 s99, s67, s17
	global_load_lds_dwordx4 v130, s[98:99]
	s_add_i32 m0, s47, 0x2000
	s_add_i32 s47, s64, s24
	s_add_u32 s98, s66, s20
	s_addc_u32 s99, s67, s21
	global_load_lds_dwordx4 v130, s[98:99]
	s_mov_b32 m0, s47
	s_add_u32 s98, s66, s34
	s_addc_u32 s99, s67, s35
	global_load_lds_dwordx4 v130, s[98:99]
	s_add_i32 m0, s47, 0x2000
	s_nop 0
	s_add_u32 s98, s66, s36
	s_addc_u32 s99, s67, s37
	global_load_lds_dwordx4 v130, s[98:99]
	s_mov_b32 m0, s51
	s_nop 0
	s_add_u32 s98, s100, s16
	s_addc_u32 s99, s101, s17
	global_load_lds_dwordx4 v128, s[98:99]
	s_mov_b32 m0, s52
	s_nop 0
	s_add_u32 s98, s100, s20
	s_addc_u32 s99, s101, s21
	global_load_lds_dwordx4 v128, s[98:99]
	s_waitcnt vmcnt(8)
	s_waitcnt lgkmcnt(0)
	s_barrier
	s_setprio 1
	s_waitcnt lgkmcnt(0)
	v_mfma_f32_16x16x32_bf16 v[60:63], v[138:141], v[174:177], v[60:63]
	v_mfma_f32_16x16x32_bf16 v[56:59], v[146:149], v[174:177], v[56:59]
	v_mfma_f32_16x16x32_bf16 v[52:55], v[138:141], v[182:185], v[52:55]
	v_mfma_f32_16x16x32_bf16 v[48:51], v[146:149], v[182:185], v[48:51]
	v_mfma_f32_16x16x32_bf16 v[44:47], v[138:141], v[190:193], v[44:47]
	v_mfma_f32_16x16x32_bf16 v[40:43], v[146:149], v[190:193], v[40:43]
	v_mfma_f32_16x16x32_bf16 v[36:39], v[138:141], v[198:201], v[36:39]
	v_mfma_f32_16x16x32_bf16 v[32:35], v[146:149], v[198:201], v[32:35]
	v_mfma_f32_16x16x32_bf16 v[60:63], v[142:145], v[178:181], v[60:63]
	v_mfma_f32_16x16x32_bf16 v[56:59], v[154:157], v[178:181], v[56:59]
	v_mfma_f32_16x16x32_bf16 v[52:55], v[142:145], v[186:189], v[52:55]
	v_mfma_f32_16x16x32_bf16 v[48:51], v[154:157], v[186:189], v[48:51]
	v_mfma_f32_16x16x32_bf16 v[44:47], v[142:145], v[194:197], v[44:47]
	v_mfma_f32_16x16x32_bf16 v[40:43], v[154:157], v[194:197], v[40:43]
	v_mfma_f32_16x16x32_bf16 v[36:39], v[142:145], v[202:205], v[36:39]
	v_mfma_f32_16x16x32_bf16 v[32:35], v[154:157], v[202:205], v[32:35]
	s_setprio 0
	s_setprio 1
	v_mfma_f32_16x16x32_bf16 v[28:31], v[158:161], v[174:177], v[28:31]
	v_mfma_f32_16x16x32_bf16 v[24:27], v[166:169], v[174:177], v[24:27]
	v_mfma_f32_16x16x32_bf16 v[20:23], v[158:161], v[182:185], v[20:23]
	v_mfma_f32_16x16x32_bf16 v[16:19], v[166:169], v[182:185], v[16:19]
	v_mfma_f32_16x16x32_bf16 v[12:15], v[158:161], v[190:193], v[12:15]
	v_mfma_f32_16x16x32_bf16 v[8:11], v[166:169], v[190:193], v[8:11]
	v_mfma_f32_16x16x32_bf16 v[4:7], v[158:161], v[198:201], v[4:7]
	v_mfma_f32_16x16x32_bf16 v[0:3], v[166:169], v[198:201], v[0:3]
	v_mfma_f32_16x16x32_bf16 v[28:31], v[162:165], v[178:181], v[28:31]
	v_mfma_f32_16x16x32_bf16 v[24:27], v[170:173], v[178:181], v[24:27]
	v_mfma_f32_16x16x32_bf16 v[20:23], v[162:165], v[186:189], v[20:23]
	v_mfma_f32_16x16x32_bf16 v[16:19], v[170:173], v[186:189], v[16:19]
	s_setprio 2
	s_barrier
	v_mfma_f32_16x16x32_bf16 v[12:15], v[162:165], v[194:197], v[12:15]
	v_mfma_f32_16x16x32_bf16 v[8:11], v[170:173], v[194:197], v[8:11]
	v_mfma_f32_16x16x32_bf16 v[4:7], v[162:165], v[202:205], v[4:7]
	v_mfma_f32_16x16x32_bf16 v[0:3], v[170:173], v[202:205], v[0:3]
	s_setprio 0
	s_add_i32 s46, s46, 2
	s_add_u32 s62, s62, 0x100
	s_addc_u32 s63, s63, 0
	s_add_u32 s44, s44, 0x100
	s_addc_u32 s45, s45, 0
	s_cmpk_gt_u32 s46, 0xa9
	s_cbranch_scc0 .LBB0_1034
	s_and_b64 vcc, exec, s[38:39]
	s_cbranch_vccz .LBB0_1037
	s_barrier

.LBB0_1180:
	ds_read_b128 v[112:115], v181
	ds_read_b128 v[116:119], v181 offset:1024
	ds_read_b128 v[128:131], v181 offset:2048
	ds_read_b128 v[142:145], v181 offset:3072
	ds_read_b128 v[146:149], v202
	ds_read_b128 v[150:153], v202 offset:1024
	ds_read_b128 v[154:157], v202 offset:2048
	ds_read_b128 v[168:171], v202 offset:3072
	s_add_u32 s49, s46, 0xfff80080
	s_addc_u32 s70, s47, -1
	s_cmp_eq_u32 s48, 28
	s_cselect_b32 s71, s39, s70
	s_cselect_b32 s70, s66, s49
	s_cselect_b32 s73, s37, s69
	s_cselect_b32 s72, s67, s68
	s_add_i32 m0, s45, 0xc000
	ds_read_b128 v[172:175], v203
	ds_read_b128 v[182:185], v203 offset:1024
	ds_read_b128 v[186:189], v203 offset:2048
	ds_read_b128 v[190:193], v203 offset:3072
	ds_read_b128 v[194:197], v203 offset:4096
	ds_read_b128 v[198:201], v203 offset:5120
	ds_read_b128 v[206:209], v203 offset:6144
	ds_read_b128 v[210:213], v203 offset:7168
	global_load_lds_dwordx4 v162, s[46:47]
	s_add_i32 m0, s45, 0xe000
	s_nop 0
	s_add_u32 s98, s46, s2
	s_addc_u32 s99, s47, s3
	global_load_lds_dwordx4 v162, s[98:99]
	s_waitcnt vmcnt(8)
	s_waitcnt lgkmcnt(0)
	s_barrier
	s_setprio 1
	s_waitcnt lgkmcnt(0)
	v_mfma_i32_16x16x64_i8 v[138:141], v[112:115], v[172:175], v[138:141]
	v_mfma_i32_16x16x64_i8 v[132:135], v[128:131], v[172:175], v[134:137]
	v_mfma_i32_16x16x64_i8 v[124:127], v[112:115], v[186:189], v[124:127]
	v_mfma_i32_16x16x64_i8 v[120:123], v[128:131], v[186:189], v[120:123]
	v_mfma_i32_16x16x64_i8 v[108:111], v[112:115], v[194:197], v[108:111]
	v_mfma_i32_16x16x64_i8 v[104:107], v[128:131], v[194:197], v[104:107]
	v_mfma_i32_16x16x64_i8 v[100:103], v[112:115], v[206:209], v[100:103]
	v_mfma_i32_16x16x64_i8 v[96:99], v[128:131], v[206:209], v[96:99]
	v_mfma_i32_16x16x64_i8 v[138:141], v[116:119], v[182:185], v[138:141]
	v_mfma_i32_16x16x64_i8 v[132:135], v[142:145], v[182:185], v[132:135]
	v_mfma_i32_16x16x64_i8 v[124:127], v[116:119], v[190:193], v[124:127]
	v_mfma_i32_16x16x64_i8 v[120:123], v[142:145], v[190:193], v[120:123]
	v_mfma_i32_16x16x64_i8 v[108:111], v[116:119], v[198:201], v[108:111]
	v_mfma_i32_16x16x64_i8 v[104:107], v[142:145], v[198:201], v[104:107]
	v_mfma_i32_16x16x64_i8 v[100:103], v[116:119], v[210:213], v[100:103]
	v_mfma_i32_16x16x64_i8 v[96:99], v[142:145], v[210:213], v[96:99]
	s_setprio 0
	s_setprio 1
	v_mfma_i32_16x16x64_i8 v[60:63], v[146:149], v[172:175], v[60:63]
	v_mfma_i32_16x16x64_i8 v[56:59], v[154:157], v[172:175], v[56:59]
	v_mfma_i32_16x16x64_i8 v[52:55], v[146:149], v[186:189], v[52:55]
	v_mfma_i32_16x16x64_i8 v[48:51], v[154:157], v[186:189], v[48:51]
	v_mfma_i32_16x16x64_i8 v[44:47], v[146:149], v[194:197], v[44:47]
	v_mfma_i32_16x16x64_i8 v[40:43], v[154:157], v[194:197], v[40:43]
	v_mfma_i32_16x16x64_i8 v[36:39], v[146:149], v[206:209], v[36:39]
	v_mfma_i32_16x16x64_i8 v[32:35], v[154:157], v[206:209], v[32:35]
	v_mfma_i32_16x16x64_i8 v[60:63], v[150:153], v[182:185], v[60:63]
	v_mfma_i32_16x16x64_i8 v[56:59], v[168:171], v[182:185], v[56:59]
	v_mfma_i32_16x16x64_i8 v[52:55], v[150:153], v[190:193], v[52:55]
	v_mfma_i32_16x16x64_i8 v[48:51], v[168:171], v[190:193], v[48:51]
	s_setprio 2
	s_barrier
	v_mfma_i32_16x16x64_i8 v[44:47], v[150:153], v[198:201], v[44:47]
	v_mfma_i32_16x16x64_i8 v[40:43], v[168:171], v[198:201], v[40:43]
	v_mfma_i32_16x16x64_i8 v[36:39], v[150:153], v[210:213], v[36:39]
	v_mfma_i32_16x16x64_i8 v[32:35], v[168:171], v[210:213], v[32:35]
	s_setprio 0
	s_add_i32 s49, s61, s33
	s_mov_b32 m0, s49
	ds_read_b128 v[172:175], v203 offset:16384
	ds_read_b128 v[182:185], v203 offset:17408
	ds_read_b128 v[186:189], v203 offset:18432
	ds_read_b128 v[190:193], v203 offset:19456
	ds_read_b128 v[194:197], v203 offset:20480
	ds_read_b128 v[198:201], v203 offset:21504
	ds_read_b128 v[206:209], v203 offset:22528
	ds_read_b128 v[210:213], v203 offset:23552
	global_load_lds_dwordx4 v160, s[72:73]
	s_add_i32 m0, s49, 0x2000
	s_add_i32 s49, s62, s33
	s_add_u32 s98, s72, s2
	s_addc_u32 s99, s73, s3
	global_load_lds_dwordx4 v160, s[98:99]
	s_mov_b32 m0, s49
	s_mov_b64 s[100:101], s[70:71]
	s_add_u32 s98, s72, s6
	s_addc_u32 s99, s73, s7
	global_load_lds_dwordx4 v160, s[98:99]
	s_add_i32 m0, s49, 0x2000
	s_nop 0
	s_add_u32 s98, s72, s8
	s_addc_u32 s99, s73, s9
	global_load_lds_dwordx4 v160, s[98:99]
	s_mov_b32 m0, s45
	s_nop 0
	global_load_lds_dwordx4 v158, s[70:71]
	s_mov_b32 m0, s50
	s_nop 0
	s_add_u32 s98, s70, s2
	s_addc_u32 s99, s71, s3
	global_load_lds_dwordx4 v158, s[98:99]
	s_waitcnt vmcnt(8)
	s_waitcnt lgkmcnt(0)
	s_barrier
	s_setprio 1
	s_waitcnt lgkmcnt(0)
	v_mfma_i32_16x16x64_i8 v[92:95], v[112:115], v[172:175], v[92:95]
	v_mfma_i32_16x16x64_i8 v[88:91], v[128:131], v[172:175], v[88:91]
	v_mfma_i32_16x16x64_i8 v[84:87], v[112:115], v[186:189], v[84:87]
	v_mfma_i32_16x16x64_i8 v[80:83], v[128:131], v[186:189], v[80:83]
	v_mfma_i32_16x16x64_i8 v[76:79], v[112:115], v[194:197], v[76:79]
	v_mfma_i32_16x16x64_i8 v[72:75], v[128:131], v[194:197], v[72:75]
	v_mfma_i32_16x16x64_i8 v[68:71], v[112:115], v[206:209], v[68:71]
	v_mfma_i32_16x16x64_i8 v[64:67], v[128:131], v[206:209], v[64:67]
	v_mfma_i32_16x16x64_i8 v[92:95], v[116:119], v[182:185], v[92:95]
	v_mfma_i32_16x16x64_i8 v[88:91], v[142:145], v[182:185], v[88:91]
	v_mfma_i32_16x16x64_i8 v[84:87], v[116:119], v[190:193], v[84:87]
	v_mfma_i32_16x16x64_i8 v[80:83], v[142:145], v[190:193], v[80:83]
	v_mfma_i32_16x16x64_i8 v[76:79], v[116:119], v[198:201], v[76:79]
	v_mfma_i32_16x16x64_i8 v[72:75], v[142:145], v[198:201], v[72:75]
	v_mfma_i32_16x16x64_i8 v[68:71], v[116:119], v[210:213], v[68:71]
	v_mfma_i32_16x16x64_i8 v[64:67], v[142:145], v[210:213], v[64:67]
	s_setprio 0
	s_setprio 1
	v_mfma_i32_16x16x64_i8 v[28:31], v[146:149], v[172:175], v[28:31]
	v_mfma_i32_16x16x64_i8 v[24:27], v[154:157], v[172:175], v[24:27]
	v_mfma_i32_16x16x64_i8 v[20:23], v[146:149], v[186:189], v[20:23]
	v_mfma_i32_16x16x64_i8 v[16:19], v[154:157], v[186:189], v[16:19]
	v_mfma_i32_16x16x64_i8 v[12:15], v[146:149], v[194:197], v[12:15]
	v_mfma_i32_16x16x64_i8 v[8:11], v[154:157], v[194:197], v[8:11]
	v_mfma_i32_16x16x64_i8 v[4:7], v[146:149], v[206:209], v[4:7]
	v_mfma_i32_16x16x64_i8 v[0:3], v[154:157], v[206:209], v[0:3]
	v_mfma_i32_16x16x64_i8 v[28:31], v[150:153], v[182:185], v[28:31]
	v_mfma_i32_16x16x64_i8 v[24:27], v[168:171], v[182:185], v[24:27]
	v_mfma_i32_16x16x64_i8 v[20:23], v[150:153], v[190:193], v[20:23]
	v_mfma_i32_16x16x64_i8 v[16:19], v[168:171], v[190:193], v[16:19]
	s_setprio 2
	s_barrier
	v_mfma_i32_16x16x64_i8 v[12:15], v[150:153], v[198:201], v[12:15]
	v_mfma_i32_16x16x64_i8 v[8:11], v[168:171], v[198:201], v[8:11]
	v_mfma_i32_16x16x64_i8 v[4:7], v[150:153], v[210:213], v[4:7]
	v_mfma_i32_16x16x64_i8 v[0:3], v[168:171], v[210:213], v[0:3]
	s_setprio 0
	s_add_i32 s49, 0, 0x18000
	v_add_u32_e32 v136, s49, v179
	s_add_i32 s70, 0, 0x1c000
	ds_read_b128 v[112:115], v136
	ds_read_b128 v[116:119], v136 offset:1024
	ds_read_b128 v[128:131], v136 offset:2048
	ds_read_b128 v[142:145], v136 offset:3072
	v_add_u32_e32 v136, s70, v179
	ds_read_b128 v[146:149], v136
	ds_read_b128 v[150:153], v136 offset:1024
	ds_read_b128 v[154:157], v136 offset:2048
	ds_read_b128 v[168:171], v136 offset:3072
	s_mov_b32 m0, s51
	ds_read_b128 v[172:175], v203 offset:32768
	ds_read_b128 v[182:185], v203 offset:33792
	ds_read_b128 v[186:189], v203 offset:34816
	ds_read_b128 v[190:193], v203 offset:35840
	ds_read_b128 v[194:197], v203 offset:36864
	ds_read_b128 v[198:201], v203 offset:37888
	ds_read_b128 v[206:209], v203 offset:38912
	ds_read_b128 v[210:213], v203 offset:39936
	s_add_u32 s98, s100, s6
	s_addc_u32 s99, s101, s7
	global_load_lds_dwordx4 v158, s[98:99]
	s_mov_b32 m0, s52
	s_nop 0
	s_add_u32 s98, s100, s8
	s_addc_u32 s99, s101, s9
	global_load_lds_dwordx4 v158, s[98:99]
	s_waitcnt vmcnt(8)
	s_waitcnt lgkmcnt(0)
	s_barrier
	s_setprio 1
	s_waitcnt lgkmcnt(0)
	v_mfma_i32_16x16x64_i8 v[136:139], v[112:115], v[172:175], v[138:141]
	v_mfma_i32_16x16x64_i8 v[132:135], v[128:131], v[172:175], v[132:135]
	v_mfma_i32_16x16x64_i8 v[124:127], v[112:115], v[186:189], v[124:127]
	v_mfma_i32_16x16x64_i8 v[120:123], v[128:131], v[186:189], v[120:123]
	v_mfma_i32_16x16x64_i8 v[108:111], v[112:115], v[194:197], v[108:111]
	v_mfma_i32_16x16x64_i8 v[104:107], v[128:131], v[194:197], v[104:107]
	v_mfma_i32_16x16x64_i8 v[100:103], v[112:115], v[206:209], v[100:103]
	v_mfma_i32_16x16x64_i8 v[96:99], v[128:131], v[206:209], v[96:99]
	v_mfma_i32_16x16x64_i8 v[138:141], v[116:119], v[182:185], v[136:139]
	v_mfma_i32_16x16x64_i8 v[134:137], v[142:145], v[182:185], v[132:135]
	v_mfma_i32_16x16x64_i8 v[124:127], v[116:119], v[190:193], v[124:127]
	v_mfma_i32_16x16x64_i8 v[120:123], v[142:145], v[190:193], v[120:123]
	v_mfma_i32_16x16x64_i8 v[108:111], v[116:119], v[198:201], v[108:111]
	v_mfma_i32_16x16x64_i8 v[104:107], v[142:145], v[198:201], v[104:107]
	v_mfma_i32_16x16x64_i8 v[100:103], v[116:119], v[210:213], v[100:103]
	v_mfma_i32_16x16x64_i8 v[96:99], v[142:145], v[210:213], v[96:99]
	s_setprio 0
	s_setprio 1
	v_mfma_i32_16x16x64_i8 v[60:63], v[146:149], v[172:175], v[60:63]
	v_mfma_i32_16x16x64_i8 v[56:59], v[154:157], v[172:175], v[56:59]
	v_mfma_i32_16x16x64_i8 v[52:55], v[146:149], v[186:189], v[52:55]
	v_mfma_i32_16x16x64_i8 v[48:51], v[154:157], v[186:189], v[48:51]
	v_mfma_i32_16x16x64_i8 v[44:47], v[146:149], v[194:197], v[44:47]
	v_mfma_i32_16x16x64_i8 v[40:43], v[154:157], v[194:197], v[40:43]
	v_mfma_i32_16x16x64_i8 v[36:39], v[146:149], v[206:209], v[36:39]
	v_mfma_i32_16x16x64_i8 v[32:35], v[154:157], v[206:209], v[32:35]
	v_mfma_i32_16x16x64_i8 v[60:63], v[150:153], v[182:185], v[60:63]
	v_mfma_i32_16x16x64_i8 v[56:59], v[168:171], v[182:185], v[56:59]
	v_mfma_i32_16x16x64_i8 v[52:55], v[150:153], v[190:193], v[52:55]
	v_mfma_i32_16x16x64_i8 v[48:51], v[168:171], v[190:193], v[48:51]
	s_setprio 2
	s_barrier
	v_mfma_i32_16x16x64_i8 v[44:47], v[150:153], v[198:201], v[44:47]
	v_mfma_i32_16x16x64_i8 v[40:43], v[168:171], v[198:201], v[40:43]
	v_mfma_i32_16x16x64_i8 v[36:39], v[150:153], v[210:213], v[36:39]
	v_mfma_i32_16x16x64_i8 v[32:35], v[168:171], v[210:213], v[32:35]
	s_setprio 0
	s_add_i32 s49, s49, s33
	s_mov_b32 m0, s49
	ds_read_b128 v[172:175], v203 offset:49152
	ds_read_b128 v[182:185], v203 offset:50176
	ds_read_b128 v[186:189], v203 offset:51200
	ds_read_b128 v[190:193], v203 offset:52224
	ds_read_b128 v[194:197], v203 offset:53248
	ds_read_b128 v[198:201], v203 offset:54272
	ds_read_b128 v[206:209], v203 offset:55296
	ds_read_b128 v[210:213], v203 offset:56320
	s_add_u32 s98, s72, s16
	s_addc_u32 s99, s73, s17
	global_load_lds_dwordx4 v160, s[98:99]
	s_add_i32 m0, s49, 0x2000
	s_add_i32 s49, s70, s33
	s_add_u32 s98, s72, s18
	s_addc_u32 s99, s73, s19
	global_load_lds_dwordx4 v160, s[98:99]
	s_mov_b32 m0, s49
	s_nop 0
	s_add_u32 s98, s72, s20
	s_addc_u32 s99, s73, s21
	global_load_lds_dwordx4 v160, s[98:99]
	s_add_i32 m0, s49, 0x2000
	s_nop 0
	s_add_u32 s98, s72, s30
	s_addc_u32 s99, s73, s31
	global_load_lds_dwordx4 v160, s[98:99]
	s_mov_b32 m0, s54
	s_nop 0
	s_add_u32 s98, s100, s16
	s_addc_u32 s99, s101, s17
	global_load_lds_dwordx4 v158, s[98:99]
	s_mov_b32 m0, s55
	s_nop 0
	s_add_u32 s98, s100, s18
	s_addc_u32 s99, s101, s19
	global_load_lds_dwordx4 v158, s[98:99]
	s_waitcnt vmcnt(8)
	s_waitcnt lgkmcnt(0)
	s_barrier
	s_setprio 1
	s_waitcnt lgkmcnt(0)
	v_mfma_i32_16x16x64_i8 v[92:95], v[112:115], v[172:175], v[92:95]
	v_mfma_i32_16x16x64_i8 v[88:91], v[128:131], v[172:175], v[88:91]
	v_mfma_i32_16x16x64_i8 v[84:87], v[112:115], v[186:189], v[84:87]
	v_mfma_i32_16x16x64_i8 v[80:83], v[128:131], v[186:189], v[80:83]
	v_mfma_i32_16x16x64_i8 v[76:79], v[112:115], v[194:197], v[76:79]
	v_mfma_i32_16x16x64_i8 v[72:75], v[128:131], v[194:197], v[72:75]
	v_mfma_i32_16x16x64_i8 v[68:71], v[112:115], v[206:209], v[68:71]
	v_mfma_i32_16x16x64_i8 v[64:67], v[128:131], v[206:209], v[64:67]
	v_mfma_i32_16x16x64_i8 v[92:95], v[116:119], v[182:185], v[92:95]
	v_mfma_i32_16x16x64_i8 v[88:91], v[142:145], v[182:185], v[88:91]
	v_mfma_i32_16x16x64_i8 v[84:87], v[116:119], v[190:193], v[84:87]
	v_mfma_i32_16x16x64_i8 v[80:83], v[142:145], v[190:193], v[80:83]
	v_mfma_i32_16x16x64_i8 v[76:79], v[116:119], v[198:201], v[76:79]
	v_mfma_i32_16x16x64_i8 v[72:75], v[142:145], v[198:201], v[72:75]
	v_mfma_i32_16x16x64_i8 v[68:71], v[116:119], v[210:213], v[68:71]
	v_mfma_i32_16x16x64_i8 v[64:67], v[142:145], v[210:213], v[64:67]
	s_setprio 0
	s_setprio 1
	v_mfma_i32_16x16x64_i8 v[28:31], v[146:149], v[172:175], v[28:31]
	v_mfma_i32_16x16x64_i8 v[24:27], v[154:157], v[172:175], v[24:27]
	v_mfma_i32_16x16x64_i8 v[20:23], v[146:149], v[186:189], v[20:23]
	v_mfma_i32_16x16x64_i8 v[16:19], v[154:157], v[186:189], v[16:19]
	v_mfma_i32_16x16x64_i8 v[12:15], v[146:149], v[194:197], v[12:15]
	v_mfma_i32_16x16x64_i8 v[8:11], v[154:157], v[194:197], v[8:11]
	v_mfma_i32_16x16x64_i8 v[4:7], v[146:149], v[206:209], v[4:7]
	v_mfma_i32_16x16x64_i8 v[0:3], v[154:157], v[206:209], v[0:3]
	v_mfma_i32_16x16x64_i8 v[28:31], v[150:153], v[182:185], v[28:31]
	v_mfma_i32_16x16x64_i8 v[24:27], v[168:171], v[182:185], v[24:27]
	v_mfma_i32_16x16x64_i8 v[20:23], v[150:153], v[190:193], v[20:23]
	v_mfma_i32_16x16x64_i8 v[16:19], v[168:171], v[190:193], v[16:19]
	s_setprio 2
	s_barrier
	v_mfma_i32_16x16x64_i8 v[12:15], v[150:153], v[198:201], v[12:15]
	v_mfma_i32_16x16x64_i8 v[8:11], v[168:171], v[198:201], v[8:11]
	v_mfma_i32_16x16x64_i8 v[4:7], v[150:153], v[210:213], v[4:7]
	v_mfma_i32_16x16x64_i8 v[0:3], v[168:171], v[210:213], v[0:3]
	s_setprio 0
	s_add_i32 s48, s48, 2
	s_add_u32 s68, s68, 0x100
	s_addc_u32 s69, s69, 0
	s_add_u32 s46, s46, 0x100
	s_addc_u32 s47, s47, 0
	s_cmp_gt_u32 s48, 29
	s_cbranch_scc0 .LBB0_1180
	s_and_b64 vcc, exec, s[34:35]
	s_cbranch_vccz .LBB0_1183
	s_barrier
